# down GEMM with staggered wave halves (one half runs MFMAs while the other reads LDS and issues DMA); silu table fill with loads up front
# speedup vs baseline: 1.1607x; 1.0109x over previous
.Ldn_afdone:
	s_barrier
	s_lshr_b32 s1, s78, 2
	s_lshl_b32 s1, s1, 7
	s_lshl_b32 s2, s0, 8
	s_mul_i32 s3, s2, 0x1600
	s_add_u32 s68, s18, s3
	s_addc_u32 s69, s19, 0
	s_mul_i32 s3, s1, 0x1600
	s_add_u32 s70, s80, s3
	s_addc_u32 s71, s81, 0
	s_lshl_b32 s3, s2, 11
	s_lshl_b32 s12, s1, 1
	s_add_u32 s3, s3, s12
	s_add_u32 s74, s24, s3
	s_addc_u32 s75, s25, 0
	s_add_i32 s12, s0, -12
	s_lshr_b32 s12, s12, 2
	s_cmp_lt_u32 s0, 16
	s_cselect_b32 s12, 0, s12
	s_cselect_b32 s14, s52, s54
	s_cselect_b32 s15, s53, s55
	s_mul_i32 s13, s82, 5
	s_add_i32 s12, s12, s13
	s_mul_i32 s12, s12, 0x6000
	s_add_u32 s12, s12, 0x5000
	s_lshl_b32 s13, s1, 2
	s_add_u32 s12, s12, s13
	s_add_u32 s72, s30, s12
	s_addc_u32 s73, s31, 0
	s_and_b32 s12, s0, 15
	s_lshl_b32 s12, s12, 20
	s_add_u32 s12, s12, s13
	s_add_u32 s14, s14, s12
	s_addc_u32 s15, s15, 0
	s_add_u32 m0, s76, 0x0
	s_nop 0
	global_load_lds_dwordx4 v196, s[68:69]
	s_add_u32 m0, s76, 0x2000
	s_nop 0
	global_load_lds_dwordx4 v197, s[68:69]
	s_add_u32 m0, s76, 0x4000
	s_nop 0
	global_load_lds_dwordx4 v198, s[68:69]
	s_add_u32 m0, s76, 0x6000
	s_nop 0
	global_load_lds_dwordx4 v199, s[68:69]
	s_add_u32 m0, s76, 0x8000
	s_nop 0
	global_load_lds_dwordx4 v196, s[70:71]
	s_add_u32 m0, s76, 0xa000
	s_nop 0
	global_load_lds_dwordx4 v197, s[70:71]
	s_add_u32 s68, s68, 0x80
	s_addc_u32 s69, s69, 0
	s_add_u32 s70, s70, 0x80
	s_addc_u32 s71, s71, 0
	s_add_u32 m0, s76, 0xc000
	s_nop 0
	global_load_lds_dwordx4 v196, s[68:69]
	s_add_u32 m0, s76, 0xe000
	s_nop 0
	global_load_lds_dwordx4 v197, s[68:69]
	s_add_u32 m0, s76, 0x10000
	s_nop 0
	global_load_lds_dwordx4 v198, s[68:69]
	s_add_u32 m0, s76, 0x12000
	s_nop 0
	global_load_lds_dwordx4 v199, s[68:69]
	s_add_u32 m0, s76, 0x14000
	s_nop 0
	global_load_lds_dwordx4 v196, s[70:71]
	s_add_u32 m0, s76, 0x16000
	s_nop 0
	global_load_lds_dwordx4 v197, s[70:71]
	s_add_u32 s68, s68, 0x80
	s_addc_u32 s69, s69, 0
	s_add_u32 s70, s70, 0x80
	s_addc_u32 s71, s71, 0
	s_waitcnt vmcnt(6)
	s_barrier
	s_cmp_ge_u32 s76, 0x1000
	s_cbranch_scc1 .Ldn_streamB
	v_add_u32_e32 v204, 0x0, v200
	v_add_u32_e32 v205, 0x0, v202
	ds_read_b128 v[130:133], v204 offset:0
	ds_read_b128 v[134:137], v204 offset:2048
	ds_read_b128 v[138:141], v204 offset:4096
	ds_read_b128 v[142:145], v204 offset:6144
	ds_read_b128 v[146:149], v205 offset:0
	ds_read_b128 v[150:153], v205 offset:2048
	ds_read_b128 v[154:157], v205 offset:4096
	ds_read_b128 v[158:161], v205 offset:6144
	v_add_u32_e32 v204, 0x0, v201
	v_add_u32_e32 v205, 0x0, v203
	ds_read_b128 v[212:215], v204 offset:0
	ds_read_b128 v[216:219], v204 offset:2048
	ds_read_b128 v[220:223], v204 offset:4096
	ds_read_b128 v[224:227], v204 offset:6144
	ds_read_b128 v[228:231], v205 offset:0
	ds_read_b128 v[232:235], v205 offset:2048
	ds_read_b128 v[236:239], v205 offset:4096
	ds_read_b128 v[240:243], v205 offset:6144
	s_add_u32 m0, s76, 0x18000
	s_nop 0
	global_load_lds_dwordx4 v196, s[68:69]
	s_add_u32 m0, s76, 0x1a000
	s_nop 0
	global_load_lds_dwordx4 v197, s[68:69]
	s_add_u32 m0, s76, 0x1c000
	s_nop 0
	global_load_lds_dwordx4 v198, s[68:69]
	s_add_u32 m0, s76, 0x1e000
	s_nop 0
	global_load_lds_dwordx4 v199, s[68:69]
	s_add_u32 m0, s76, 0x20000
	s_nop 0
	global_load_lds_dwordx4 v196, s[70:71]
	s_add_u32 m0, s76, 0x22000
	s_nop 0
	global_load_lds_dwordx4 v197, s[70:71]
	s_add_u32 s68, s68, 0x80
	s_addc_u32 s69, s69, 0
	s_add_u32 s70, s70, 0x80
	s_addc_u32 s71, s71, 0
	global_load_dwordx4 v[174:177], v190, s[72:73] offset:0
	global_load_dwordx4 v[178:181], v190, s[72:73] offset:64
	global_load_dwordx4 v[182:185], v190, s[72:73] offset:128
	global_load_dwordx4 v[186:189], v190, s[72:73] offset:192
	global_load_dwordx2 v[66:67], v206, s[74:75] offset:0
	global_load_dwordx2 v[70:71], v206, s[74:75] offset:32
	global_load_dwordx2 v[74:75], v206, s[74:75] offset:64
	s_waitcnt lgkmcnt(0)
	s_barrier
	v_mfma_f32_16x16x32_bf16 v[2:5], v[146:149], v[130:133], 0
	v_mfma_f32_16x16x32_bf16 v[6:9], v[150:153], v[130:133], 0
	v_mfma_f32_16x16x32_bf16 v[10:13], v[154:157], v[130:133], 0
	v_mfma_f32_16x16x32_bf16 v[14:17], v[158:161], v[130:133], 0
	v_mfma_f32_16x16x32_bf16 v[18:21], v[146:149], v[134:137], 0
	v_mfma_f32_16x16x32_bf16 v[22:25], v[150:153], v[134:137], 0
	v_mfma_f32_16x16x32_bf16 v[26:29], v[154:157], v[134:137], 0
	v_mfma_f32_16x16x32_bf16 v[30:33], v[158:161], v[134:137], 0
	v_mfma_f32_16x16x32_bf16 v[34:37], v[146:149], v[138:141], 0
	v_mfma_f32_16x16x32_bf16 v[38:41], v[150:153], v[138:141], 0
	v_mfma_f32_16x16x32_bf16 v[42:45], v[154:157], v[138:141], 0
	v_mfma_f32_16x16x32_bf16 v[46:49], v[158:161], v[138:141], 0
	v_mfma_f32_16x16x32_bf16 v[50:53], v[146:149], v[142:145], 0
	v_mfma_f32_16x16x32_bf16 v[54:57], v[150:153], v[142:145], 0
	v_mfma_f32_16x16x32_bf16 v[58:61], v[154:157], v[142:145], 0
	v_mfma_f32_16x16x32_bf16 v[62:65], v[158:161], v[142:145], 0
	v_mfma_f32_16x16x32_bf16 v[2:5], v[228:231], v[212:215], v[2:5]
	v_mfma_f32_16x16x32_bf16 v[6:9], v[232:235], v[212:215], v[6:9]
	v_mfma_f32_16x16x32_bf16 v[10:13], v[236:239], v[212:215], v[10:13]
	v_mfma_f32_16x16x32_bf16 v[14:17], v[240:243], v[212:215], v[14:17]
	v_mfma_f32_16x16x32_bf16 v[18:21], v[228:231], v[216:219], v[18:21]
	v_mfma_f32_16x16x32_bf16 v[22:25], v[232:235], v[216:219], v[22:25]
	v_mfma_f32_16x16x32_bf16 v[26:29], v[236:239], v[216:219], v[26:29]
	v_mfma_f32_16x16x32_bf16 v[30:33], v[240:243], v[216:219], v[30:33]
	v_mfma_f32_16x16x32_bf16 v[34:37], v[228:231], v[220:223], v[34:37]
	v_mfma_f32_16x16x32_bf16 v[38:41], v[232:235], v[220:223], v[38:41]
	v_mfma_f32_16x16x32_bf16 v[42:45], v[236:239], v[220:223], v[42:45]
	v_mfma_f32_16x16x32_bf16 v[46:49], v[240:243], v[220:223], v[46:49]
	v_mfma_f32_16x16x32_bf16 v[50:53], v[228:231], v[224:227], v[50:53]
	v_mfma_f32_16x16x32_bf16 v[54:57], v[232:235], v[224:227], v[54:57]
	v_mfma_f32_16x16x32_bf16 v[58:61], v[236:239], v[224:227], v[58:61]
	v_mfma_f32_16x16x32_bf16 v[62:65], v[240:243], v[224:227], v[62:65]
	s_waitcnt vmcnt(13)
	s_barrier
	v_add_u32_e32 v204, 0xc000, v200
	v_add_u32_e32 v205, 0xc000, v202
	ds_read_b128 v[130:133], v204 offset:0
	ds_read_b128 v[134:137], v204 offset:2048
	ds_read_b128 v[138:141], v204 offset:4096
	ds_read_b128 v[142:145], v204 offset:6144
	ds_read_b128 v[146:149], v205 offset:0
	ds_read_b128 v[150:153], v205 offset:2048
	ds_read_b128 v[154:157], v205 offset:4096
	ds_read_b128 v[158:161], v205 offset:6144
	v_add_u32_e32 v204, 0xc000, v201
	v_add_u32_e32 v205, 0xc000, v203
	ds_read_b128 v[212:215], v204 offset:0
	ds_read_b128 v[216:219], v204 offset:2048
	ds_read_b128 v[220:223], v204 offset:4096
	ds_read_b128 v[224:227], v204 offset:6144
	ds_read_b128 v[228:231], v205 offset:0
	ds_read_b128 v[232:235], v205 offset:2048
	ds_read_b128 v[236:239], v205 offset:4096
	ds_read_b128 v[240:243], v205 offset:6144
	s_add_u32 m0, s76, 0x0
	s_nop 0
	global_load_lds_dwordx4 v196, s[68:69]
	s_add_u32 m0, s76, 0x2000
	s_nop 0
	global_load_lds_dwordx4 v197, s[68:69]
	s_add_u32 m0, s76, 0x4000
	s_nop 0
	global_load_lds_dwordx4 v198, s[68:69]
	s_add_u32 m0, s76, 0x6000
	s_nop 0
	global_load_lds_dwordx4 v199, s[68:69]
	s_add_u32 m0, s76, 0x8000
	s_nop 0
	global_load_lds_dwordx4 v196, s[70:71]
	s_add_u32 m0, s76, 0xa000
	s_nop 0
	global_load_lds_dwordx4 v197, s[70:71]
	s_add_u32 s68, s68, 0x80
	s_addc_u32 s69, s69, 0
	s_add_u32 s70, s70, 0x80
	s_addc_u32 s71, s71, 0
	global_load_dwordx2 v[78:79], v206, s[74:75] offset:96
	global_load_dwordx2 v[82:83], v207, s[74:75] offset:0
	global_load_dwordx2 v[86:87], v207, s[74:75] offset:32
	global_load_dwordx2 v[90:91], v207, s[74:75] offset:64
	global_load_dwordx2 v[94:95], v207, s[74:75] offset:96
	global_load_dwordx2 v[98:99], v208, s[74:75] offset:0
	global_load_dwordx2 v[102:103], v208, s[74:75] offset:32
	s_waitcnt lgkmcnt(0)
	s_barrier
	v_mfma_f32_16x16x32_bf16 v[2:5], v[146:149], v[130:133], v[2:5]
	v_mfma_f32_16x16x32_bf16 v[6:9], v[150:153], v[130:133], v[6:9]
	v_mfma_f32_16x16x32_bf16 v[10:13], v[154:157], v[130:133], v[10:13]
	v_mfma_f32_16x16x32_bf16 v[14:17], v[158:161], v[130:133], v[14:17]
	v_mfma_f32_16x16x32_bf16 v[18:21], v[146:149], v[134:137], v[18:21]
	v_mfma_f32_16x16x32_bf16 v[22:25], v[150:153], v[134:137], v[22:25]
	v_mfma_f32_16x16x32_bf16 v[26:29], v[154:157], v[134:137], v[26:29]
	v_mfma_f32_16x16x32_bf16 v[30:33], v[158:161], v[134:137], v[30:33]
	v_mfma_f32_16x16x32_bf16 v[34:37], v[146:149], v[138:141], v[34:37]
	v_mfma_f32_16x16x32_bf16 v[38:41], v[150:153], v[138:141], v[38:41]
	v_mfma_f32_16x16x32_bf16 v[42:45], v[154:157], v[138:141], v[42:45]
	v_mfma_f32_16x16x32_bf16 v[46:49], v[158:161], v[138:141], v[46:49]
	v_mfma_f32_16x16x32_bf16 v[50:53], v[146:149], v[142:145], v[50:53]
	v_mfma_f32_16x16x32_bf16 v[54:57], v[150:153], v[142:145], v[54:57]
	v_mfma_f32_16x16x32_bf16 v[58:61], v[154:157], v[142:145], v[58:61]
	v_mfma_f32_16x16x32_bf16 v[62:65], v[158:161], v[142:145], v[62:65]
	v_mfma_f32_16x16x32_bf16 v[2:5], v[228:231], v[212:215], v[2:5]
	v_mfma_f32_16x16x32_bf16 v[6:9], v[232:235], v[212:215], v[6:9]
	v_mfma_f32_16x16x32_bf16 v[10:13], v[236:239], v[212:215], v[10:13]
	v_mfma_f32_16x16x32_bf16 v[14:17], v[240:243], v[212:215], v[14:17]
	v_mfma_f32_16x16x32_bf16 v[18:21], v[228:231], v[216:219], v[18:21]
	v_mfma_f32_16x16x32_bf16 v[22:25], v[232:235], v[216:219], v[22:25]
	v_mfma_f32_16x16x32_bf16 v[26:29], v[236:239], v[216:219], v[26:29]
	v_mfma_f32_16x16x32_bf16 v[30:33], v[240:243], v[216:219], v[30:33]
	v_mfma_f32_16x16x32_bf16 v[34:37], v[228:231], v[220:223], v[34:37]
	v_mfma_f32_16x16x32_bf16 v[38:41], v[232:235], v[220:223], v[38:41]
	v_mfma_f32_16x16x32_bf16 v[42:45], v[236:239], v[220:223], v[42:45]
	v_mfma_f32_16x16x32_bf16 v[46:49], v[240:243], v[220:223], v[46:49]
	v_mfma_f32_16x16x32_bf16 v[50:53], v[228:231], v[224:227], v[50:53]
	v_mfma_f32_16x16x32_bf16 v[54:57], v[232:235], v[224:227], v[54:57]
	v_mfma_f32_16x16x32_bf16 v[58:61], v[236:239], v[224:227], v[58:61]
	v_mfma_f32_16x16x32_bf16 v[62:65], v[240:243], v[224:227], v[62:65]
	s_waitcnt vmcnt(20)
	s_barrier
	v_add_u32_e32 v204, 0x18000, v200
	v_add_u32_e32 v205, 0x18000, v202
	ds_read_b128 v[130:133], v204 offset:0
	ds_read_b128 v[134:137], v204 offset:2048
	ds_read_b128 v[138:141], v204 offset:4096
	ds_read_b128 v[142:145], v204 offset:6144
	ds_read_b128 v[146:149], v205 offset:0
	ds_read_b128 v[150:153], v205 offset:2048
	ds_read_b128 v[154:157], v205 offset:4096
	ds_read_b128 v[158:161], v205 offset:6144
	v_add_u32_e32 v204, 0x18000, v201
	v_add_u32_e32 v205, 0x18000, v203
	ds_read_b128 v[212:215], v204 offset:0
	ds_read_b128 v[216:219], v204 offset:2048
	ds_read_b128 v[220:223], v204 offset:4096
	ds_read_b128 v[224:227], v204 offset:6144
	ds_read_b128 v[228:231], v205 offset:0
	ds_read_b128 v[232:235], v205 offset:2048
	ds_read_b128 v[236:239], v205 offset:4096
	ds_read_b128 v[240:243], v205 offset:6144
	s_add_u32 m0, s76, 0xc000
	s_nop 0
	global_load_lds_dwordx4 v196, s[68:69]
	s_add_u32 m0, s76, 0xe000
	s_nop 0
	global_load_lds_dwordx4 v197, s[68:69]
	s_add_u32 m0, s76, 0x10000
	s_nop 0
	global_load_lds_dwordx4 v198, s[68:69]
	s_add_u32 m0, s76, 0x12000
	s_nop 0
	global_load_lds_dwordx4 v199, s[68:69]
	s_add_u32 m0, s76, 0x14000
	s_nop 0
	global_load_lds_dwordx4 v196, s[70:71]
	s_add_u32 m0, s76, 0x16000
	s_nop 0
	global_load_lds_dwordx4 v197, s[70:71]
	s_add_u32 s68, s68, 0x80
	s_addc_u32 s69, s69, 0
	s_add_u32 s70, s70, 0x80
	s_addc_u32 s71, s71, 0
	global_load_dwordx2 v[106:107], v208, s[74:75] offset:64
	global_load_dwordx2 v[110:111], v208, s[74:75] offset:96
	global_load_dwordx2 v[114:115], v209, s[74:75] offset:0
	global_load_dwordx2 v[118:119], v209, s[74:75] offset:32
	global_load_dwordx2 v[122:123], v209, s[74:75] offset:64
	global_load_dwordx2 v[126:127], v209, s[74:75] offset:96
	s_waitcnt lgkmcnt(0)
	s_barrier
	v_mfma_f32_16x16x32_bf16 v[2:5], v[146:149], v[130:133], v[2:5]
	v_mfma_f32_16x16x32_bf16 v[6:9], v[150:153], v[130:133], v[6:9]
	v_mfma_f32_16x16x32_bf16 v[10:13], v[154:157], v[130:133], v[10:13]
	v_mfma_f32_16x16x32_bf16 v[14:17], v[158:161], v[130:133], v[14:17]
	v_mfma_f32_16x16x32_bf16 v[18:21], v[146:149], v[134:137], v[18:21]
	v_mfma_f32_16x16x32_bf16 v[22:25], v[150:153], v[134:137], v[22:25]
	v_mfma_f32_16x16x32_bf16 v[26:29], v[154:157], v[134:137], v[26:29]
	v_mfma_f32_16x16x32_bf16 v[30:33], v[158:161], v[134:137], v[30:33]
	v_mfma_f32_16x16x32_bf16 v[34:37], v[146:149], v[138:141], v[34:37]
	v_mfma_f32_16x16x32_bf16 v[38:41], v[150:153], v[138:141], v[38:41]
	v_mfma_f32_16x16x32_bf16 v[42:45], v[154:157], v[138:141], v[42:45]
	v_mfma_f32_16x16x32_bf16 v[46:49], v[158:161], v[138:141], v[46:49]
	v_mfma_f32_16x16x32_bf16 v[50:53], v[146:149], v[142:145], v[50:53]
	v_mfma_f32_16x16x32_bf16 v[54:57], v[150:153], v[142:145], v[54:57]
	v_mfma_f32_16x16x32_bf16 v[58:61], v[154:157], v[142:145], v[58:61]
	v_mfma_f32_16x16x32_bf16 v[62:65], v[158:161], v[142:145], v[62:65]
	v_mfma_f32_16x16x32_bf16 v[2:5], v[228:231], v[212:215], v[2:5]
	v_mfma_f32_16x16x32_bf16 v[6:9], v[232:235], v[212:215], v[6:9]
	v_mfma_f32_16x16x32_bf16 v[10:13], v[236:239], v[212:215], v[10:13]
	v_mfma_f32_16x16x32_bf16 v[14:17], v[240:243], v[212:215], v[14:17]
	v_mfma_f32_16x16x32_bf16 v[18:21], v[228:231], v[216:219], v[18:21]
	v_mfma_f32_16x16x32_bf16 v[22:25], v[232:235], v[216:219], v[22:25]
	v_mfma_f32_16x16x32_bf16 v[26:29], v[236:239], v[216:219], v[26:29]
	v_mfma_f32_16x16x32_bf16 v[30:33], v[240:243], v[216:219], v[30:33]
	v_mfma_f32_16x16x32_bf16 v[34:37], v[228:231], v[220:223], v[34:37]
	v_mfma_f32_16x16x32_bf16 v[38:41], v[232:235], v[220:223], v[38:41]
	v_mfma_f32_16x16x32_bf16 v[42:45], v[236:239], v[220:223], v[42:45]
	v_mfma_f32_16x16x32_bf16 v[46:49], v[240:243], v[220:223], v[46:49]
	v_mfma_f32_16x16x32_bf16 v[50:53], v[228:231], v[224:227], v[50:53]
	v_mfma_f32_16x16x32_bf16 v[54:57], v[232:235], v[224:227], v[54:57]
	v_mfma_f32_16x16x32_bf16 v[58:61], v[236:239], v[224:227], v[58:61]
	v_mfma_f32_16x16x32_bf16 v[62:65], v[240:243], v[224:227], v[62:65]
	s_waitcnt vmcnt(19)
	s_barrier
	v_add_u32_e32 v204, 0x0, v200
	v_add_u32_e32 v205, 0x0, v202
	ds_read_b128 v[130:133], v204 offset:0
	ds_read_b128 v[134:137], v204 offset:2048
	ds_read_b128 v[138:141], v204 offset:4096
	ds_read_b128 v[142:145], v204 offset:6144
	ds_read_b128 v[146:149], v205 offset:0
	ds_read_b128 v[150:153], v205 offset:2048
	ds_read_b128 v[154:157], v205 offset:4096
	ds_read_b128 v[158:161], v205 offset:6144
	v_add_u32_e32 v204, 0x0, v201
	v_add_u32_e32 v205, 0x0, v203
	ds_read_b128 v[212:215], v204 offset:0
	ds_read_b128 v[216:219], v204 offset:2048
	ds_read_b128 v[220:223], v204 offset:4096
	ds_read_b128 v[224:227], v204 offset:6144
	ds_read_b128 v[228:231], v205 offset:0
	ds_read_b128 v[232:235], v205 offset:2048
	ds_read_b128 v[236:239], v205 offset:4096
	ds_read_b128 v[240:243], v205 offset:6144
	s_add_u32 m0, s76, 0x18000
	s_nop 0
	global_load_lds_dwordx4 v196, s[68:69]
	s_add_u32 m0, s76, 0x1a000
	s_nop 0
	global_load_lds_dwordx4 v197, s[68:69]
	s_add_u32 m0, s76, 0x1c000
	s_nop 0
	global_load_lds_dwordx4 v198, s[68:69]
	s_add_u32 m0, s76, 0x1e000
	s_nop 0
	global_load_lds_dwordx4 v199, s[68:69]
	s_add_u32 m0, s76, 0x20000
	s_nop 0
	global_load_lds_dwordx4 v196, s[70:71]
	s_add_u32 m0, s76, 0x22000
	s_nop 0
	global_load_lds_dwordx4 v197, s[70:71]
	s_add_u32 s68, s68, 0x80
	s_addc_u32 s69, s69, 0
	s_add_u32 s70, s70, 0x80
	s_addc_u32 s71, s71, 0
	s_waitcnt lgkmcnt(0)
	s_barrier
	v_mfma_f32_16x16x32_bf16 v[2:5], v[146:149], v[130:133], v[2:5]
	v_mfma_f32_16x16x32_bf16 v[6:9], v[150:153], v[130:133], v[6:9]
	v_mfma_f32_16x16x32_bf16 v[10:13], v[154:157], v[130:133], v[10:13]
	v_mfma_f32_16x16x32_bf16 v[14:17], v[158:161], v[130:133], v[14:17]
	v_mfma_f32_16x16x32_bf16 v[18:21], v[146:149], v[134:137], v[18:21]
	v_mfma_f32_16x16x32_bf16 v[22:25], v[150:153], v[134:137], v[22:25]
	v_mfma_f32_16x16x32_bf16 v[26:29], v[154:157], v[134:137], v[26:29]
	v_mfma_f32_16x16x32_bf16 v[30:33], v[158:161], v[134:137], v[30:33]
	v_mfma_f32_16x16x32_bf16 v[34:37], v[146:149], v[138:141], v[34:37]
	v_mfma_f32_16x16x32_bf16 v[38:41], v[150:153], v[138:141], v[38:41]
	v_mfma_f32_16x16x32_bf16 v[42:45], v[154:157], v[138:141], v[42:45]
	v_mfma_f32_16x16x32_bf16 v[46:49], v[158:161], v[138:141], v[46:49]
	v_mfma_f32_16x16x32_bf16 v[50:53], v[146:149], v[142:145], v[50:53]
	v_mfma_f32_16x16x32_bf16 v[54:57], v[150:153], v[142:145], v[54:57]
	v_mfma_f32_16x16x32_bf16 v[58:61], v[154:157], v[142:145], v[58:61]
	v_mfma_f32_16x16x32_bf16 v[62:65], v[158:161], v[142:145], v[62:65]
	v_mfma_f32_16x16x32_bf16 v[2:5], v[228:231], v[212:215], v[2:5]
	v_mfma_f32_16x16x32_bf16 v[6:9], v[232:235], v[212:215], v[6:9]
	v_mfma_f32_16x16x32_bf16 v[10:13], v[236:239], v[212:215], v[10:13]
	v_mfma_f32_16x16x32_bf16 v[14:17], v[240:243], v[212:215], v[14:17]
	v_mfma_f32_16x16x32_bf16 v[18:21], v[228:231], v[216:219], v[18:21]
	v_mfma_f32_16x16x32_bf16 v[22:25], v[232:235], v[216:219], v[22:25]
	v_mfma_f32_16x16x32_bf16 v[26:29], v[236:239], v[216:219], v[26:29]
	v_mfma_f32_16x16x32_bf16 v[30:33], v[240:243], v[216:219], v[30:33]
	v_mfma_f32_16x16x32_bf16 v[34:37], v[228:231], v[220:223], v[34:37]
	v_mfma_f32_16x16x32_bf16 v[38:41], v[232:235], v[220:223], v[38:41]
	v_mfma_f32_16x16x32_bf16 v[42:45], v[236:239], v[220:223], v[42:45]
	v_mfma_f32_16x16x32_bf16 v[46:49], v[240:243], v[220:223], v[46:49]
	v_mfma_f32_16x16x32_bf16 v[50:53], v[228:231], v[224:227], v[50:53]
	v_mfma_f32_16x16x32_bf16 v[54:57], v[232:235], v[224:227], v[54:57]
	v_mfma_f32_16x16x32_bf16 v[58:61], v[236:239], v[224:227], v[58:61]
	v_mfma_f32_16x16x32_bf16 v[62:65], v[240:243], v[224:227], v[62:65]
	s_waitcnt vmcnt(12)
	s_barrier
	v_add_u32_e32 v204, 0xc000, v200
	v_add_u32_e32 v205, 0xc000, v202
	ds_read_b128 v[130:133], v204 offset:0
	ds_read_b128 v[134:137], v204 offset:2048
	ds_read_b128 v[138:141], v204 offset:4096
	ds_read_b128 v[142:145], v204 offset:6144
	ds_read_b128 v[146:149], v205 offset:0
	ds_read_b128 v[150:153], v205 offset:2048
	ds_read_b128 v[154:157], v205 offset:4096
	ds_read_b128 v[158:161], v205 offset:6144
	v_add_u32_e32 v204, 0xc000, v201
	v_add_u32_e32 v205, 0xc000, v203
	ds_read_b128 v[212:215], v204 offset:0
	ds_read_b128 v[216:219], v204 offset:2048
	ds_read_b128 v[220:223], v204 offset:4096
	ds_read_b128 v[224:227], v204 offset:6144
	ds_read_b128 v[228:231], v205 offset:0
	ds_read_b128 v[232:235], v205 offset:2048
	ds_read_b128 v[236:239], v205 offset:4096
	ds_read_b128 v[240:243], v205 offset:6144
	s_add_u32 m0, s76, 0x0
	s_nop 0
	global_load_lds_dwordx4 v196, s[68:69]
	s_add_u32 m0, s76, 0x2000
	s_nop 0
	global_load_lds_dwordx4 v197, s[68:69]
	s_add_u32 m0, s76, 0x4000
	s_nop 0
	global_load_lds_dwordx4 v198, s[68:69]
	s_add_u32 m0, s76, 0x6000
	s_nop 0
	global_load_lds_dwordx4 v199, s[68:69]
	s_add_u32 m0, s76, 0x8000
	s_nop 0
	global_load_lds_dwordx4 v196, s[70:71]
	s_add_u32 m0, s76, 0xa000
	s_nop 0
	global_load_lds_dwordx4 v197, s[70:71]
	s_add_u32 s68, s68, 0x80
	s_addc_u32 s69, s69, 0
	s_add_u32 s70, s70, 0x80
	s_addc_u32 s71, s71, 0
	s_waitcnt lgkmcnt(0)
	s_barrier
	v_mfma_f32_16x16x32_bf16 v[2:5], v[146:149], v[130:133], v[2:5]
	v_mfma_f32_16x16x32_bf16 v[6:9], v[150:153], v[130:133], v[6:9]
	v_mfma_f32_16x16x32_bf16 v[10:13], v[154:157], v[130:133], v[10:13]
	v_mfma_f32_16x16x32_bf16 v[14:17], v[158:161], v[130:133], v[14:17]
	v_mfma_f32_16x16x32_bf16 v[18:21], v[146:149], v[134:137], v[18:21]
	v_mfma_f32_16x16x32_bf16 v[22:25], v[150:153], v[134:137], v[22:25]
	v_mfma_f32_16x16x32_bf16 v[26:29], v[154:157], v[134:137], v[26:29]
	v_mfma_f32_16x16x32_bf16 v[30:33], v[158:161], v[134:137], v[30:33]
	v_mfma_f32_16x16x32_bf16 v[34:37], v[146:149], v[138:141], v[34:37]
	v_mfma_f32_16x16x32_bf16 v[38:41], v[150:153], v[138:141], v[38:41]
	v_mfma_f32_16x16x32_bf16 v[42:45], v[154:157], v[138:141], v[42:45]
	v_mfma_f32_16x16x32_bf16 v[46:49], v[158:161], v[138:141], v[46:49]
	v_mfma_f32_16x16x32_bf16 v[50:53], v[146:149], v[142:145], v[50:53]
	v_mfma_f32_16x16x32_bf16 v[54:57], v[150:153], v[142:145], v[54:57]
	v_mfma_f32_16x16x32_bf16 v[58:61], v[154:157], v[142:145], v[58:61]
	v_mfma_f32_16x16x32_bf16 v[62:65], v[158:161], v[142:145], v[62:65]
	v_mfma_f32_16x16x32_bf16 v[2:5], v[228:231], v[212:215], v[2:5]
	v_mfma_f32_16x16x32_bf16 v[6:9], v[232:235], v[212:215], v[6:9]
	v_mfma_f32_16x16x32_bf16 v[10:13], v[236:239], v[212:215], v[10:13]
	v_mfma_f32_16x16x32_bf16 v[14:17], v[240:243], v[212:215], v[14:17]
	v_mfma_f32_16x16x32_bf16 v[18:21], v[228:231], v[216:219], v[18:21]
	v_mfma_f32_16x16x32_bf16 v[22:25], v[232:235], v[216:219], v[22:25]
	v_mfma_f32_16x16x32_bf16 v[26:29], v[236:239], v[216:219], v[26:29]
	v_mfma_f32_16x16x32_bf16 v[30:33], v[240:243], v[216:219], v[30:33]
	v_mfma_f32_16x16x32_bf16 v[34:37], v[228:231], v[220:223], v[34:37]
	v_mfma_f32_16x16x32_bf16 v[38:41], v[232:235], v[220:223], v[38:41]
	v_mfma_f32_16x16x32_bf16 v[42:45], v[236:239], v[220:223], v[42:45]
	v_mfma_f32_16x16x32_bf16 v[46:49], v[240:243], v[220:223], v[46:49]
	v_mfma_f32_16x16x32_bf16 v[50:53], v[228:231], v[224:227], v[50:53]
	v_mfma_f32_16x16x32_bf16 v[54:57], v[232:235], v[224:227], v[54:57]
	v_mfma_f32_16x16x32_bf16 v[58:61], v[236:239], v[224:227], v[58:61]
	v_mfma_f32_16x16x32_bf16 v[62:65], v[240:243], v[224:227], v[62:65]
	s_waitcnt vmcnt(6)
	s_barrier
	s_mov_b32 s16, 12
.Ldn_kloop1:
	v_add_u32_e32 v204, 0x18000, v200
	v_add_u32_e32 v205, 0x18000, v202
	ds_read_b128 v[130:133], v204 offset:0
	ds_read_b128 v[134:137], v204 offset:2048
	ds_read_b128 v[138:141], v204 offset:4096
	ds_read_b128 v[142:145], v204 offset:6144
	ds_read_b128 v[146:149], v205 offset:0
	ds_read_b128 v[150:153], v205 offset:2048
	ds_read_b128 v[154:157], v205 offset:4096
	ds_read_b128 v[158:161], v205 offset:6144
	v_add_u32_e32 v204, 0x18000, v201
	v_add_u32_e32 v205, 0x18000, v203
	ds_read_b128 v[212:215], v204 offset:0
	ds_read_b128 v[216:219], v204 offset:2048
	ds_read_b128 v[220:223], v204 offset:4096
	ds_read_b128 v[224:227], v204 offset:6144
	ds_read_b128 v[228:231], v205 offset:0
	ds_read_b128 v[232:235], v205 offset:2048
	ds_read_b128 v[236:239], v205 offset:4096
	ds_read_b128 v[240:243], v205 offset:6144
	s_add_u32 m0, s76, 0xc000
	s_nop 0
	global_load_lds_dwordx4 v196, s[68:69]
	s_add_u32 m0, s76, 0xe000
	s_nop 0
	global_load_lds_dwordx4 v197, s[68:69]
	s_add_u32 m0, s76, 0x10000
	s_nop 0
	global_load_lds_dwordx4 v198, s[68:69]
	s_add_u32 m0, s76, 0x12000
	s_nop 0
	global_load_lds_dwordx4 v199, s[68:69]
	s_add_u32 m0, s76, 0x14000
	s_nop 0
	global_load_lds_dwordx4 v196, s[70:71]
	s_add_u32 m0, s76, 0x16000
	s_nop 0
	global_load_lds_dwordx4 v197, s[70:71]
	s_add_u32 s68, s68, 0x80
	s_addc_u32 s69, s69, 0
	s_add_u32 s70, s70, 0x80
	s_addc_u32 s71, s71, 0
	s_waitcnt lgkmcnt(0)
	s_barrier
	v_mfma_f32_16x16x32_bf16 v[2:5], v[146:149], v[130:133], v[2:5]
	v_mfma_f32_16x16x32_bf16 v[6:9], v[150:153], v[130:133], v[6:9]
	v_mfma_f32_16x16x32_bf16 v[10:13], v[154:157], v[130:133], v[10:13]
	v_mfma_f32_16x16x32_bf16 v[14:17], v[158:161], v[130:133], v[14:17]
	v_mfma_f32_16x16x32_bf16 v[18:21], v[146:149], v[134:137], v[18:21]
	v_mfma_f32_16x16x32_bf16 v[22:25], v[150:153], v[134:137], v[22:25]
	v_mfma_f32_16x16x32_bf16 v[26:29], v[154:157], v[134:137], v[26:29]
	v_mfma_f32_16x16x32_bf16 v[30:33], v[158:161], v[134:137], v[30:33]
	v_mfma_f32_16x16x32_bf16 v[34:37], v[146:149], v[138:141], v[34:37]
	v_mfma_f32_16x16x32_bf16 v[38:41], v[150:153], v[138:141], v[38:41]
	v_mfma_f32_16x16x32_bf16 v[42:45], v[154:157], v[138:141], v[42:45]
	v_mfma_f32_16x16x32_bf16 v[46:49], v[158:161], v[138:141], v[46:49]
	v_mfma_f32_16x16x32_bf16 v[50:53], v[146:149], v[142:145], v[50:53]
	v_mfma_f32_16x16x32_bf16 v[54:57], v[150:153], v[142:145], v[54:57]
	v_mfma_f32_16x16x32_bf16 v[58:61], v[154:157], v[142:145], v[58:61]
	v_mfma_f32_16x16x32_bf16 v[62:65], v[158:161], v[142:145], v[62:65]
	v_mfma_f32_16x16x32_bf16 v[2:5], v[228:231], v[212:215], v[2:5]
	v_mfma_f32_16x16x32_bf16 v[6:9], v[232:235], v[212:215], v[6:9]
	v_mfma_f32_16x16x32_bf16 v[10:13], v[236:239], v[212:215], v[10:13]
	v_mfma_f32_16x16x32_bf16 v[14:17], v[240:243], v[212:215], v[14:17]
	v_mfma_f32_16x16x32_bf16 v[18:21], v[228:231], v[216:219], v[18:21]
	v_mfma_f32_16x16x32_bf16 v[22:25], v[232:235], v[216:219], v[22:25]
	v_mfma_f32_16x16x32_bf16 v[26:29], v[236:239], v[216:219], v[26:29]
	v_mfma_f32_16x16x32_bf16 v[30:33], v[240:243], v[216:219], v[30:33]
	v_mfma_f32_16x16x32_bf16 v[34:37], v[228:231], v[220:223], v[34:37]
	v_mfma_f32_16x16x32_bf16 v[38:41], v[232:235], v[220:223], v[38:41]
	v_mfma_f32_16x16x32_bf16 v[42:45], v[236:239], v[220:223], v[42:45]
	v_mfma_f32_16x16x32_bf16 v[46:49], v[240:243], v[220:223], v[46:49]
	v_mfma_f32_16x16x32_bf16 v[50:53], v[228:231], v[224:227], v[50:53]
	v_mfma_f32_16x16x32_bf16 v[54:57], v[232:235], v[224:227], v[54:57]
	v_mfma_f32_16x16x32_bf16 v[58:61], v[236:239], v[224:227], v[58:61]
	v_mfma_f32_16x16x32_bf16 v[62:65], v[240:243], v[224:227], v[62:65]
	s_waitcnt vmcnt(6)
	s_barrier
	v_add_u32_e32 v204, 0x0, v200
	v_add_u32_e32 v205, 0x0, v202
	ds_read_b128 v[130:133], v204 offset:0
	ds_read_b128 v[134:137], v204 offset:2048
	ds_read_b128 v[138:141], v204 offset:4096
	ds_read_b128 v[142:145], v204 offset:6144
	ds_read_b128 v[146:149], v205 offset:0
	ds_read_b128 v[150:153], v205 offset:2048
	ds_read_b128 v[154:157], v205 offset:4096
	ds_read_b128 v[158:161], v205 offset:6144
	v_add_u32_e32 v204, 0x0, v201
	v_add_u32_e32 v205, 0x0, v203
	ds_read_b128 v[212:215], v204 offset:0
	ds_read_b128 v[216:219], v204 offset:2048
	ds_read_b128 v[220:223], v204 offset:4096
	ds_read_b128 v[224:227], v204 offset:6144
	ds_read_b128 v[228:231], v205 offset:0
	ds_read_b128 v[232:235], v205 offset:2048
	ds_read_b128 v[236:239], v205 offset:4096
	ds_read_b128 v[240:243], v205 offset:6144
	s_add_u32 m0, s76, 0x18000
	s_nop 0
	global_load_lds_dwordx4 v196, s[68:69]
	s_add_u32 m0, s76, 0x1a000
	s_nop 0
	global_load_lds_dwordx4 v197, s[68:69]
	s_add_u32 m0, s76, 0x1c000
	s_nop 0
	global_load_lds_dwordx4 v198, s[68:69]
	s_add_u32 m0, s76, 0x1e000
	s_nop 0
	global_load_lds_dwordx4 v199, s[68:69]
	s_add_u32 m0, s76, 0x20000
	s_nop 0
	global_load_lds_dwordx4 v196, s[70:71]
	s_add_u32 m0, s76, 0x22000
	s_nop 0
	global_load_lds_dwordx4 v197, s[70:71]
	s_add_u32 s68, s68, 0x80
	s_addc_u32 s69, s69, 0
	s_add_u32 s70, s70, 0x80
	s_addc_u32 s71, s71, 0
	s_waitcnt lgkmcnt(0)
	s_barrier
	v_mfma_f32_16x16x32_bf16 v[2:5], v[146:149], v[130:133], v[2:5]
	v_mfma_f32_16x16x32_bf16 v[6:9], v[150:153], v[130:133], v[6:9]
	v_mfma_f32_16x16x32_bf16 v[10:13], v[154:157], v[130:133], v[10:13]
	v_mfma_f32_16x16x32_bf16 v[14:17], v[158:161], v[130:133], v[14:17]
	v_mfma_f32_16x16x32_bf16 v[18:21], v[146:149], v[134:137], v[18:21]
	v_mfma_f32_16x16x32_bf16 v[22:25], v[150:153], v[134:137], v[22:25]
	v_mfma_f32_16x16x32_bf16 v[26:29], v[154:157], v[134:137], v[26:29]
	v_mfma_f32_16x16x32_bf16 v[30:33], v[158:161], v[134:137], v[30:33]
	v_mfma_f32_16x16x32_bf16 v[34:37], v[146:149], v[138:141], v[34:37]
	v_mfma_f32_16x16x32_bf16 v[38:41], v[150:153], v[138:141], v[38:41]
	v_mfma_f32_16x16x32_bf16 v[42:45], v[154:157], v[138:141], v[42:45]
	v_mfma_f32_16x16x32_bf16 v[46:49], v[158:161], v[138:141], v[46:49]
	v_mfma_f32_16x16x32_bf16 v[50:53], v[146:149], v[142:145], v[50:53]
	v_mfma_f32_16x16x32_bf16 v[54:57], v[150:153], v[142:145], v[54:57]
	v_mfma_f32_16x16x32_bf16 v[58:61], v[154:157], v[142:145], v[58:61]
	v_mfma_f32_16x16x32_bf16 v[62:65], v[158:161], v[142:145], v[62:65]
	v_mfma_f32_16x16x32_bf16 v[2:5], v[228:231], v[212:215], v[2:5]
	v_mfma_f32_16x16x32_bf16 v[6:9], v[232:235], v[212:215], v[6:9]
	v_mfma_f32_16x16x32_bf16 v[10:13], v[236:239], v[212:215], v[10:13]
	v_mfma_f32_16x16x32_bf16 v[14:17], v[240:243], v[212:215], v[14:17]
	v_mfma_f32_16x16x32_bf16 v[18:21], v[228:231], v[216:219], v[18:21]
	v_mfma_f32_16x16x32_bf16 v[22:25], v[232:235], v[216:219], v[22:25]
	v_mfma_f32_16x16x32_bf16 v[26:29], v[236:239], v[216:219], v[26:29]
	v_mfma_f32_16x16x32_bf16 v[30:33], v[240:243], v[216:219], v[30:33]
	v_mfma_f32_16x16x32_bf16 v[34:37], v[228:231], v[220:223], v[34:37]
	v_mfma_f32_16x16x32_bf16 v[38:41], v[232:235], v[220:223], v[38:41]
	v_mfma_f32_16x16x32_bf16 v[42:45], v[236:239], v[220:223], v[42:45]
	v_mfma_f32_16x16x32_bf16 v[46:49], v[240:243], v[220:223], v[46:49]
	v_mfma_f32_16x16x32_bf16 v[50:53], v[228:231], v[224:227], v[50:53]
	v_mfma_f32_16x16x32_bf16 v[54:57], v[232:235], v[224:227], v[54:57]
	v_mfma_f32_16x16x32_bf16 v[58:61], v[236:239], v[224:227], v[58:61]
	v_mfma_f32_16x16x32_bf16 v[62:65], v[240:243], v[224:227], v[62:65]
	s_waitcnt vmcnt(6)
	s_barrier
	v_add_u32_e32 v204, 0xc000, v200
	v_add_u32_e32 v205, 0xc000, v202
	ds_read_b128 v[130:133], v204 offset:0
	ds_read_b128 v[134:137], v204 offset:2048
	ds_read_b128 v[138:141], v204 offset:4096
	ds_read_b128 v[142:145], v204 offset:6144
	ds_read_b128 v[146:149], v205 offset:0
	ds_read_b128 v[150:153], v205 offset:2048
	ds_read_b128 v[154:157], v205 offset:4096
	ds_read_b128 v[158:161], v205 offset:6144
	v_add_u32_e32 v204, 0xc000, v201
	v_add_u32_e32 v205, 0xc000, v203
	ds_read_b128 v[212:215], v204 offset:0
	ds_read_b128 v[216:219], v204 offset:2048
	ds_read_b128 v[220:223], v204 offset:4096
	ds_read_b128 v[224:227], v204 offset:6144
	ds_read_b128 v[228:231], v205 offset:0
	ds_read_b128 v[232:235], v205 offset:2048
	ds_read_b128 v[236:239], v205 offset:4096
	ds_read_b128 v[240:243], v205 offset:6144
	s_add_u32 m0, s76, 0x0
	s_nop 0
	global_load_lds_dwordx4 v196, s[68:69]
	s_add_u32 m0, s76, 0x2000
	s_nop 0
	global_load_lds_dwordx4 v197, s[68:69]
	s_add_u32 m0, s76, 0x4000
	s_nop 0
	global_load_lds_dwordx4 v198, s[68:69]
	s_add_u32 m0, s76, 0x6000
	s_nop 0
	global_load_lds_dwordx4 v199, s[68:69]
	s_add_u32 m0, s76, 0x8000
	s_nop 0
	global_load_lds_dwordx4 v196, s[70:71]
	s_add_u32 m0, s76, 0xa000
	s_nop 0
	global_load_lds_dwordx4 v197, s[70:71]
	s_add_u32 s68, s68, 0x80
	s_addc_u32 s69, s69, 0
	s_add_u32 s70, s70, 0x80
	s_addc_u32 s71, s71, 0
	s_waitcnt lgkmcnt(0)
	s_barrier
	v_mfma_f32_16x16x32_bf16 v[2:5], v[146:149], v[130:133], v[2:5]
	v_mfma_f32_16x16x32_bf16 v[6:9], v[150:153], v[130:133], v[6:9]
	v_mfma_f32_16x16x32_bf16 v[10:13], v[154:157], v[130:133], v[10:13]
	v_mfma_f32_16x16x32_bf16 v[14:17], v[158:161], v[130:133], v[14:17]
	v_mfma_f32_16x16x32_bf16 v[18:21], v[146:149], v[134:137], v[18:21]
	v_mfma_f32_16x16x32_bf16 v[22:25], v[150:153], v[134:137], v[22:25]
	v_mfma_f32_16x16x32_bf16 v[26:29], v[154:157], v[134:137], v[26:29]
	v_mfma_f32_16x16x32_bf16 v[30:33], v[158:161], v[134:137], v[30:33]
	v_mfma_f32_16x16x32_bf16 v[34:37], v[146:149], v[138:141], v[34:37]
	v_mfma_f32_16x16x32_bf16 v[38:41], v[150:153], v[138:141], v[38:41]
	v_mfma_f32_16x16x32_bf16 v[42:45], v[154:157], v[138:141], v[42:45]
	v_mfma_f32_16x16x32_bf16 v[46:49], v[158:161], v[138:141], v[46:49]
	v_mfma_f32_16x16x32_bf16 v[50:53], v[146:149], v[142:145], v[50:53]
	v_mfma_f32_16x16x32_bf16 v[54:57], v[150:153], v[142:145], v[54:57]
	v_mfma_f32_16x16x32_bf16 v[58:61], v[154:157], v[142:145], v[58:61]
	v_mfma_f32_16x16x32_bf16 v[62:65], v[158:161], v[142:145], v[62:65]
	v_mfma_f32_16x16x32_bf16 v[2:5], v[228:231], v[212:215], v[2:5]
	v_mfma_f32_16x16x32_bf16 v[6:9], v[232:235], v[212:215], v[6:9]
	v_mfma_f32_16x16x32_bf16 v[10:13], v[236:239], v[212:215], v[10:13]
	v_mfma_f32_16x16x32_bf16 v[14:17], v[240:243], v[212:215], v[14:17]
	v_mfma_f32_16x16x32_bf16 v[18:21], v[228:231], v[216:219], v[18:21]
	v_mfma_f32_16x16x32_bf16 v[22:25], v[232:235], v[216:219], v[22:25]
	v_mfma_f32_16x16x32_bf16 v[26:29], v[236:239], v[216:219], v[26:29]
	v_mfma_f32_16x16x32_bf16 v[30:33], v[240:243], v[216:219], v[30:33]
	v_mfma_f32_16x16x32_bf16 v[34:37], v[228:231], v[220:223], v[34:37]
	v_mfma_f32_16x16x32_bf16 v[38:41], v[232:235], v[220:223], v[38:41]
	v_mfma_f32_16x16x32_bf16 v[42:45], v[236:239], v[220:223], v[42:45]
	v_mfma_f32_16x16x32_bf16 v[46:49], v[240:243], v[220:223], v[46:49]
	v_mfma_f32_16x16x32_bf16 v[50:53], v[228:231], v[224:227], v[50:53]
	v_mfma_f32_16x16x32_bf16 v[54:57], v[232:235], v[224:227], v[54:57]
	v_mfma_f32_16x16x32_bf16 v[58:61], v[236:239], v[224:227], v[58:61]
	v_mfma_f32_16x16x32_bf16 v[62:65], v[240:243], v[224:227], v[62:65]
	s_waitcnt vmcnt(6)
	s_barrier
	s_add_i32 s16, s16, -1
	s_cmp_lg_u32 s16, 0
	s_cbranch_scc1 .Ldn_kloop1
	v_add_u32_e32 v204, 0x18000, v200
	v_add_u32_e32 v205, 0x18000, v202
	ds_read_b128 v[130:133], v204 offset:0
	ds_read_b128 v[134:137], v204 offset:2048
	ds_read_b128 v[138:141], v204 offset:4096
	ds_read_b128 v[142:145], v204 offset:6144
	ds_read_b128 v[146:149], v205 offset:0
	ds_read_b128 v[150:153], v205 offset:2048
	ds_read_b128 v[154:157], v205 offset:4096
	ds_read_b128 v[158:161], v205 offset:6144
	v_add_u32_e32 v204, 0x18000, v201
	v_add_u32_e32 v205, 0x18000, v203
	ds_read_b128 v[212:215], v204 offset:0
	ds_read_b128 v[216:219], v204 offset:2048
	ds_read_b128 v[220:223], v204 offset:4096
	ds_read_b128 v[224:227], v204 offset:6144
	ds_read_b128 v[228:231], v205 offset:0
	ds_read_b128 v[232:235], v205 offset:2048
	ds_read_b128 v[236:239], v205 offset:4096
	ds_read_b128 v[240:243], v205 offset:6144
	s_add_u32 m0, s76, 0xc000
	s_nop 0
	global_load_lds_dwordx4 v196, s[68:69]
	s_add_u32 m0, s76, 0xe000
	s_nop 0
	global_load_lds_dwordx4 v197, s[68:69]
	s_add_u32 m0, s76, 0x10000
	s_nop 0
	global_load_lds_dwordx4 v198, s[68:69]
	s_add_u32 m0, s76, 0x12000
	s_nop 0
	global_load_lds_dwordx4 v199, s[68:69]
	s_add_u32 m0, s76, 0x14000
	s_nop 0
	global_load_lds_dwordx4 v196, s[70:71]
	s_add_u32 m0, s76, 0x16000
	s_nop 0
	global_load_lds_dwordx4 v197, s[70:71]
	s_add_u32 s68, s68, 0x80
	s_addc_u32 s69, s69, 0
	s_add_u32 s70, s70, 0x80
	s_addc_u32 s71, s71, 0
	s_waitcnt lgkmcnt(0)
	s_barrier
	v_mfma_f32_16x16x32_bf16 v[2:5], v[146:149], v[130:133], v[2:5]
	v_mfma_f32_16x16x32_bf16 v[6:9], v[150:153], v[130:133], v[6:9]
	v_mfma_f32_16x16x32_bf16 v[10:13], v[154:157], v[130:133], v[10:13]
	v_mfma_f32_16x16x32_bf16 v[14:17], v[158:161], v[130:133], v[14:17]
	v_mfma_f32_16x16x32_bf16 v[18:21], v[146:149], v[134:137], v[18:21]
	v_mfma_f32_16x16x32_bf16 v[22:25], v[150:153], v[134:137], v[22:25]
	v_mfma_f32_16x16x32_bf16 v[26:29], v[154:157], v[134:137], v[26:29]
	v_mfma_f32_16x16x32_bf16 v[30:33], v[158:161], v[134:137], v[30:33]
	v_mfma_f32_16x16x32_bf16 v[34:37], v[146:149], v[138:141], v[34:37]
	v_mfma_f32_16x16x32_bf16 v[38:41], v[150:153], v[138:141], v[38:41]
	v_mfma_f32_16x16x32_bf16 v[42:45], v[154:157], v[138:141], v[42:45]
	v_mfma_f32_16x16x32_bf16 v[46:49], v[158:161], v[138:141], v[46:49]
	v_mfma_f32_16x16x32_bf16 v[50:53], v[146:149], v[142:145], v[50:53]
	v_mfma_f32_16x16x32_bf16 v[54:57], v[150:153], v[142:145], v[54:57]
	v_mfma_f32_16x16x32_bf16 v[58:61], v[154:157], v[142:145], v[58:61]
	v_mfma_f32_16x16x32_bf16 v[62:65], v[158:161], v[142:145], v[62:65]
	v_mfma_f32_16x16x32_bf16 v[2:5], v[228:231], v[212:215], v[2:5]
	v_mfma_f32_16x16x32_bf16 v[6:9], v[232:235], v[212:215], v[6:9]
	v_mfma_f32_16x16x32_bf16 v[10:13], v[236:239], v[212:215], v[10:13]
	v_mfma_f32_16x16x32_bf16 v[14:17], v[240:243], v[212:215], v[14:17]
	v_mfma_f32_16x16x32_bf16 v[18:21], v[228:231], v[216:219], v[18:21]
	v_mfma_f32_16x16x32_bf16 v[22:25], v[232:235], v[216:219], v[22:25]
	v_mfma_f32_16x16x32_bf16 v[26:29], v[236:239], v[216:219], v[26:29]
	v_mfma_f32_16x16x32_bf16 v[30:33], v[240:243], v[216:219], v[30:33]
	v_mfma_f32_16x16x32_bf16 v[34:37], v[228:231], v[220:223], v[34:37]
	v_mfma_f32_16x16x32_bf16 v[38:41], v[232:235], v[220:223], v[38:41]
	v_mfma_f32_16x16x32_bf16 v[42:45], v[236:239], v[220:223], v[42:45]
	v_mfma_f32_16x16x32_bf16 v[46:49], v[240:243], v[220:223], v[46:49]
	v_mfma_f32_16x16x32_bf16 v[50:53], v[228:231], v[224:227], v[50:53]
	v_mfma_f32_16x16x32_bf16 v[54:57], v[232:235], v[224:227], v[54:57]
	v_mfma_f32_16x16x32_bf16 v[58:61], v[236:239], v[224:227], v[58:61]
	v_mfma_f32_16x16x32_bf16 v[62:65], v[240:243], v[224:227], v[62:65]
	s_waitcnt vmcnt(6)
	s_barrier
	v_add_u32_e32 v204, 0x0, v200
	v_add_u32_e32 v205, 0x0, v202
	ds_read_b128 v[130:133], v204 offset:0
	ds_read_b128 v[134:137], v204 offset:2048
	ds_read_b128 v[138:141], v204 offset:4096
	ds_read_b128 v[142:145], v204 offset:6144
	ds_read_b128 v[146:149], v205 offset:0
	ds_read_b128 v[150:153], v205 offset:2048
	ds_read_b128 v[154:157], v205 offset:4096
	ds_read_b128 v[158:161], v205 offset:6144
	v_add_u32_e32 v204, 0x0, v201
	v_add_u32_e32 v205, 0x0, v203
	ds_read_b128 v[212:215], v204 offset:0
	ds_read_b128 v[216:219], v204 offset:2048
	ds_read_b128 v[220:223], v204 offset:4096
	ds_read_b128 v[224:227], v204 offset:6144
	ds_read_b128 v[228:231], v205 offset:0
	ds_read_b128 v[232:235], v205 offset:2048
	ds_read_b128 v[236:239], v205 offset:4096
	ds_read_b128 v[240:243], v205 offset:6144
	s_waitcnt lgkmcnt(0)
	s_barrier
	v_mfma_f32_16x16x32_bf16 v[2:5], v[146:149], v[130:133], v[2:5]
	v_mfma_f32_16x16x32_bf16 v[6:9], v[150:153], v[130:133], v[6:9]
	v_mfma_f32_16x16x32_bf16 v[10:13], v[154:157], v[130:133], v[10:13]
	v_mfma_f32_16x16x32_bf16 v[14:17], v[158:161], v[130:133], v[14:17]
	v_mfma_f32_16x16x32_bf16 v[18:21], v[146:149], v[134:137], v[18:21]
	v_mfma_f32_16x16x32_bf16 v[22:25], v[150:153], v[134:137], v[22:25]
	v_mfma_f32_16x16x32_bf16 v[26:29], v[154:157], v[134:137], v[26:29]
	v_mfma_f32_16x16x32_bf16 v[30:33], v[158:161], v[134:137], v[30:33]
	v_mfma_f32_16x16x32_bf16 v[34:37], v[146:149], v[138:141], v[34:37]
	v_mfma_f32_16x16x32_bf16 v[38:41], v[150:153], v[138:141], v[38:41]
	v_mfma_f32_16x16x32_bf16 v[42:45], v[154:157], v[138:141], v[42:45]
	v_mfma_f32_16x16x32_bf16 v[46:49], v[158:161], v[138:141], v[46:49]
	v_mfma_f32_16x16x32_bf16 v[50:53], v[146:149], v[142:145], v[50:53]
	v_mfma_f32_16x16x32_bf16 v[54:57], v[150:153], v[142:145], v[54:57]
	v_mfma_f32_16x16x32_bf16 v[58:61], v[154:157], v[142:145], v[58:61]
	v_mfma_f32_16x16x32_bf16 v[62:65], v[158:161], v[142:145], v[62:65]
	v_mfma_f32_16x16x32_bf16 v[2:5], v[228:231], v[212:215], v[2:5]
	v_mfma_f32_16x16x32_bf16 v[6:9], v[232:235], v[212:215], v[6:9]
	v_mfma_f32_16x16x32_bf16 v[10:13], v[236:239], v[212:215], v[10:13]
	v_mfma_f32_16x16x32_bf16 v[14:17], v[240:243], v[212:215], v[14:17]
	v_mfma_f32_16x16x32_bf16 v[18:21], v[228:231], v[216:219], v[18:21]
	v_mfma_f32_16x16x32_bf16 v[22:25], v[232:235], v[216:219], v[22:25]
	v_mfma_f32_16x16x32_bf16 v[26:29], v[236:239], v[216:219], v[26:29]
	v_mfma_f32_16x16x32_bf16 v[30:33], v[240:243], v[216:219], v[30:33]
	v_mfma_f32_16x16x32_bf16 v[34:37], v[228:231], v[220:223], v[34:37]
	v_mfma_f32_16x16x32_bf16 v[38:41], v[232:235], v[220:223], v[38:41]
	v_mfma_f32_16x16x32_bf16 v[42:45], v[236:239], v[220:223], v[42:45]
	v_mfma_f32_16x16x32_bf16 v[46:49], v[240:243], v[220:223], v[46:49]
	v_mfma_f32_16x16x32_bf16 v[50:53], v[228:231], v[224:227], v[50:53]
	v_mfma_f32_16x16x32_bf16 v[54:57], v[232:235], v[224:227], v[54:57]
	v_mfma_f32_16x16x32_bf16 v[58:61], v[236:239], v[224:227], v[58:61]
	v_mfma_f32_16x16x32_bf16 v[62:65], v[240:243], v[224:227], v[62:65]
	s_waitcnt vmcnt(0)
	s_barrier
	v_add_u32_e32 v204, 0xc000, v200
	v_add_u32_e32 v205, 0xc000, v202
	ds_read_b128 v[130:133], v204 offset:0
	ds_read_b128 v[134:137], v204 offset:2048
	ds_read_b128 v[138:141], v204 offset:4096
	ds_read_b128 v[142:145], v204 offset:6144
	ds_read_b128 v[146:149], v205 offset:0
	ds_read_b128 v[150:153], v205 offset:2048
	ds_read_b128 v[154:157], v205 offset:4096
	ds_read_b128 v[158:161], v205 offset:6144
	v_add_u32_e32 v204, 0xc000, v201
	v_add_u32_e32 v205, 0xc000, v203
	ds_read_b128 v[212:215], v204 offset:0
	ds_read_b128 v[216:219], v204 offset:2048
	ds_read_b128 v[220:223], v204 offset:4096
	ds_read_b128 v[224:227], v204 offset:6144
	ds_read_b128 v[228:231], v205 offset:0
	ds_read_b128 v[232:235], v205 offset:2048
	ds_read_b128 v[236:239], v205 offset:4096
	ds_read_b128 v[240:243], v205 offset:6144
	s_waitcnt lgkmcnt(0)
	s_barrier
	v_mfma_f32_16x16x32_bf16 v[2:5], v[146:149], v[130:133], v[2:5]
	v_mfma_f32_16x16x32_bf16 v[6:9], v[150:153], v[130:133], v[6:9]
	v_mfma_f32_16x16x32_bf16 v[10:13], v[154:157], v[130:133], v[10:13]
	v_mfma_f32_16x16x32_bf16 v[14:17], v[158:161], v[130:133], v[14:17]
	v_mfma_f32_16x16x32_bf16 v[18:21], v[146:149], v[134:137], v[18:21]
	v_mfma_f32_16x16x32_bf16 v[22:25], v[150:153], v[134:137], v[22:25]
	v_mfma_f32_16x16x32_bf16 v[26:29], v[154:157], v[134:137], v[26:29]
	v_mfma_f32_16x16x32_bf16 v[30:33], v[158:161], v[134:137], v[30:33]
	v_mfma_f32_16x16x32_bf16 v[34:37], v[146:149], v[138:141], v[34:37]
	v_mfma_f32_16x16x32_bf16 v[38:41], v[150:153], v[138:141], v[38:41]
	v_mfma_f32_16x16x32_bf16 v[42:45], v[154:157], v[138:141], v[42:45]
	v_mfma_f32_16x16x32_bf16 v[46:49], v[158:161], v[138:141], v[46:49]
	v_mfma_f32_16x16x32_bf16 v[50:53], v[146:149], v[142:145], v[50:53]
	v_mfma_f32_16x16x32_bf16 v[54:57], v[150:153], v[142:145], v[54:57]
	v_mfma_f32_16x16x32_bf16 v[58:61], v[154:157], v[142:145], v[58:61]
	v_mfma_f32_16x16x32_bf16 v[62:65], v[158:161], v[142:145], v[62:65]
	v_mfma_f32_16x16x32_bf16 v[2:5], v[228:231], v[212:215], v[2:5]
	v_mfma_f32_16x16x32_bf16 v[6:9], v[232:235], v[212:215], v[6:9]
	v_mfma_f32_16x16x32_bf16 v[10:13], v[236:239], v[212:215], v[10:13]
	v_mfma_f32_16x16x32_bf16 v[14:17], v[240:243], v[212:215], v[14:17]
	v_mfma_f32_16x16x32_bf16 v[18:21], v[228:231], v[216:219], v[18:21]
	v_mfma_f32_16x16x32_bf16 v[22:25], v[232:235], v[216:219], v[22:25]
	v_mfma_f32_16x16x32_bf16 v[26:29], v[236:239], v[216:219], v[26:29]
	v_mfma_f32_16x16x32_bf16 v[30:33], v[240:243], v[216:219], v[30:33]
	v_mfma_f32_16x16x32_bf16 v[34:37], v[228:231], v[220:223], v[34:37]
	v_mfma_f32_16x16x32_bf16 v[38:41], v[232:235], v[220:223], v[38:41]
	v_mfma_f32_16x16x32_bf16 v[42:45], v[236:239], v[220:223], v[42:45]
	v_mfma_f32_16x16x32_bf16 v[46:49], v[240:243], v[220:223], v[46:49]
	v_mfma_f32_16x16x32_bf16 v[50:53], v[228:231], v[224:227], v[50:53]
	v_mfma_f32_16x16x32_bf16 v[54:57], v[232:235], v[224:227], v[54:57]
	v_mfma_f32_16x16x32_bf16 v[58:61], v[236:239], v[224:227], v[58:61]
	v_mfma_f32_16x16x32_bf16 v[62:65], v[240:243], v[224:227], v[62:65]
	s_barrier
	s_branch .Ldn_join
.Ldn_streamB:
	s_barrier
	v_add_u32_e32 v204, 0x0, v200
	v_add_u32_e32 v205, 0x0, v202
	ds_read_b128 v[130:133], v204 offset:0
	ds_read_b128 v[134:137], v204 offset:2048
	ds_read_b128 v[138:141], v204 offset:4096
	ds_read_b128 v[142:145], v204 offset:6144
	ds_read_b128 v[146:149], v205 offset:0
	ds_read_b128 v[150:153], v205 offset:2048
	ds_read_b128 v[154:157], v205 offset:4096
	ds_read_b128 v[158:161], v205 offset:6144
	v_add_u32_e32 v204, 0x0, v201
	v_add_u32_e32 v205, 0x0, v203
	ds_read_b128 v[212:215], v204 offset:0
	ds_read_b128 v[216:219], v204 offset:2048
	ds_read_b128 v[220:223], v204 offset:4096
	ds_read_b128 v[224:227], v204 offset:6144
	ds_read_b128 v[228:231], v205 offset:0
	ds_read_b128 v[232:235], v205 offset:2048
	ds_read_b128 v[236:239], v205 offset:4096
	ds_read_b128 v[240:243], v205 offset:6144
	s_add_u32 m0, s76, 0x18000
	s_nop 0
	global_load_lds_dwordx4 v196, s[68:69]
	s_add_u32 m0, s76, 0x1a000
	s_nop 0
	global_load_lds_dwordx4 v197, s[68:69]
	s_add_u32 m0, s76, 0x1c000
	s_nop 0
	global_load_lds_dwordx4 v198, s[68:69]
	s_add_u32 m0, s76, 0x1e000
	s_nop 0
	global_load_lds_dwordx4 v199, s[68:69]
	s_add_u32 m0, s76, 0x20000
	s_nop 0
	global_load_lds_dwordx4 v196, s[70:71]
	s_add_u32 m0, s76, 0x22000
	s_nop 0
	global_load_lds_dwordx4 v197, s[70:71]
	s_add_u32 s68, s68, 0x80
	s_addc_u32 s69, s69, 0
	s_add_u32 s70, s70, 0x80
	s_addc_u32 s71, s71, 0
	global_load_dwordx4 v[174:177], v190, s[72:73] offset:0
	global_load_dwordx4 v[178:181], v190, s[72:73] offset:64
	global_load_dwordx4 v[182:185], v190, s[72:73] offset:128
	global_load_dwordx4 v[186:189], v190, s[72:73] offset:192
	global_load_dwordx2 v[66:67], v206, s[74:75] offset:0
	global_load_dwordx2 v[70:71], v206, s[74:75] offset:32
	global_load_dwordx2 v[74:75], v206, s[74:75] offset:64
	s_waitcnt vmcnt(13)
	s_waitcnt lgkmcnt(0)
	s_barrier
	v_mfma_f32_16x16x32_bf16 v[2:5], v[146:149], v[130:133], 0
	v_mfma_f32_16x16x32_bf16 v[6:9], v[150:153], v[130:133], 0
	v_mfma_f32_16x16x32_bf16 v[10:13], v[154:157], v[130:133], 0
	v_mfma_f32_16x16x32_bf16 v[14:17], v[158:161], v[130:133], 0
	v_mfma_f32_16x16x32_bf16 v[18:21], v[146:149], v[134:137], 0
	v_mfma_f32_16x16x32_bf16 v[22:25], v[150:153], v[134:137], 0
	v_mfma_f32_16x16x32_bf16 v[26:29], v[154:157], v[134:137], 0
	v_mfma_f32_16x16x32_bf16 v[30:33], v[158:161], v[134:137], 0
	v_mfma_f32_16x16x32_bf16 v[34:37], v[146:149], v[138:141], 0
	v_mfma_f32_16x16x32_bf16 v[38:41], v[150:153], v[138:141], 0
	v_mfma_f32_16x16x32_bf16 v[42:45], v[154:157], v[138:141], 0
	v_mfma_f32_16x16x32_bf16 v[46:49], v[158:161], v[138:141], 0
	v_mfma_f32_16x16x32_bf16 v[50:53], v[146:149], v[142:145], 0
	v_mfma_f32_16x16x32_bf16 v[54:57], v[150:153], v[142:145], 0
	v_mfma_f32_16x16x32_bf16 v[58:61], v[154:157], v[142:145], 0
	v_mfma_f32_16x16x32_bf16 v[62:65], v[158:161], v[142:145], 0
	v_mfma_f32_16x16x32_bf16 v[2:5], v[228:231], v[212:215], v[2:5]
	v_mfma_f32_16x16x32_bf16 v[6:9], v[232:235], v[212:215], v[6:9]
	v_mfma_f32_16x16x32_bf16 v[10:13], v[236:239], v[212:215], v[10:13]
	v_mfma_f32_16x16x32_bf16 v[14:17], v[240:243], v[212:215], v[14:17]
	v_mfma_f32_16x16x32_bf16 v[18:21], v[228:231], v[216:219], v[18:21]
	v_mfma_f32_16x16x32_bf16 v[22:25], v[232:235], v[216:219], v[22:25]
	v_mfma_f32_16x16x32_bf16 v[26:29], v[236:239], v[216:219], v[26:29]
	v_mfma_f32_16x16x32_bf16 v[30:33], v[240:243], v[216:219], v[30:33]
	v_mfma_f32_16x16x32_bf16 v[34:37], v[228:231], v[220:223], v[34:37]
	v_mfma_f32_16x16x32_bf16 v[38:41], v[232:235], v[220:223], v[38:41]
	v_mfma_f32_16x16x32_bf16 v[42:45], v[236:239], v[220:223], v[42:45]
	v_mfma_f32_16x16x32_bf16 v[46:49], v[240:243], v[220:223], v[46:49]
	v_mfma_f32_16x16x32_bf16 v[50:53], v[228:231], v[224:227], v[50:53]
	v_mfma_f32_16x16x32_bf16 v[54:57], v[232:235], v[224:227], v[54:57]
	v_mfma_f32_16x16x32_bf16 v[58:61], v[236:239], v[224:227], v[58:61]
	v_mfma_f32_16x16x32_bf16 v[62:65], v[240:243], v[224:227], v[62:65]
	s_barrier
	v_add_u32_e32 v204, 0xc000, v200
	v_add_u32_e32 v205, 0xc000, v202
	ds_read_b128 v[130:133], v204 offset:0
	ds_read_b128 v[134:137], v204 offset:2048
	ds_read_b128 v[138:141], v204 offset:4096
	ds_read_b128 v[142:145], v204 offset:6144
	ds_read_b128 v[146:149], v205 offset:0
	ds_read_b128 v[150:153], v205 offset:2048
	ds_read_b128 v[154:157], v205 offset:4096
	ds_read_b128 v[158:161], v205 offset:6144
	v_add_u32_e32 v204, 0xc000, v201
	v_add_u32_e32 v205, 0xc000, v203
	ds_read_b128 v[212:215], v204 offset:0
	ds_read_b128 v[216:219], v204 offset:2048
	ds_read_b128 v[220:223], v204 offset:4096
	ds_read_b128 v[224:227], v204 offset:6144
	ds_read_b128 v[228:231], v205 offset:0
	ds_read_b128 v[232:235], v205 offset:2048
	ds_read_b128 v[236:239], v205 offset:4096
	ds_read_b128 v[240:243], v205 offset:6144
	s_add_u32 m0, s76, 0x0
	s_nop 0
	global_load_lds_dwordx4 v196, s[68:69]
	s_add_u32 m0, s76, 0x2000
	s_nop 0
	global_load_lds_dwordx4 v197, s[68:69]
	s_add_u32 m0, s76, 0x4000
	s_nop 0
	global_load_lds_dwordx4 v198, s[68:69]
	s_add_u32 m0, s76, 0x6000
	s_nop 0
	global_load_lds_dwordx4 v199, s[68:69]
	s_add_u32 m0, s76, 0x8000
	s_nop 0
	global_load_lds_dwordx4 v196, s[70:71]
	s_add_u32 m0, s76, 0xa000
	s_nop 0
	global_load_lds_dwordx4 v197, s[70:71]
	s_add_u32 s68, s68, 0x80
	s_addc_u32 s69, s69, 0
	s_add_u32 s70, s70, 0x80
	s_addc_u32 s71, s71, 0
	global_load_dwordx2 v[78:79], v206, s[74:75] offset:96
	global_load_dwordx2 v[82:83], v207, s[74:75] offset:0
	global_load_dwordx2 v[86:87], v207, s[74:75] offset:32
	global_load_dwordx2 v[90:91], v207, s[74:75] offset:64
	global_load_dwordx2 v[94:95], v207, s[74:75] offset:96
	global_load_dwordx2 v[98:99], v208, s[74:75] offset:0
	global_load_dwordx2 v[102:103], v208, s[74:75] offset:32
	s_waitcnt vmcnt(20)
	s_waitcnt lgkmcnt(0)
	s_barrier
	v_mfma_f32_16x16x32_bf16 v[2:5], v[146:149], v[130:133], v[2:5]
	v_mfma_f32_16x16x32_bf16 v[6:9], v[150:153], v[130:133], v[6:9]
	v_mfma_f32_16x16x32_bf16 v[10:13], v[154:157], v[130:133], v[10:13]
	v_mfma_f32_16x16x32_bf16 v[14:17], v[158:161], v[130:133], v[14:17]
	v_mfma_f32_16x16x32_bf16 v[18:21], v[146:149], v[134:137], v[18:21]
	v_mfma_f32_16x16x32_bf16 v[22:25], v[150:153], v[134:137], v[22:25]
	v_mfma_f32_16x16x32_bf16 v[26:29], v[154:157], v[134:137], v[26:29]
	v_mfma_f32_16x16x32_bf16 v[30:33], v[158:161], v[134:137], v[30:33]
	v_mfma_f32_16x16x32_bf16 v[34:37], v[146:149], v[138:141], v[34:37]
	v_mfma_f32_16x16x32_bf16 v[38:41], v[150:153], v[138:141], v[38:41]
	v_mfma_f32_16x16x32_bf16 v[42:45], v[154:157], v[138:141], v[42:45]
	v_mfma_f32_16x16x32_bf16 v[46:49], v[158:161], v[138:141], v[46:49]
	v_mfma_f32_16x16x32_bf16 v[50:53], v[146:149], v[142:145], v[50:53]
	v_mfma_f32_16x16x32_bf16 v[54:57], v[150:153], v[142:145], v[54:57]
	v_mfma_f32_16x16x32_bf16 v[58:61], v[154:157], v[142:145], v[58:61]
	v_mfma_f32_16x16x32_bf16 v[62:65], v[158:161], v[142:145], v[62:65]
	v_mfma_f32_16x16x32_bf16 v[2:5], v[228:231], v[212:215], v[2:5]
	v_mfma_f32_16x16x32_bf16 v[6:9], v[232:235], v[212:215], v[6:9]
	v_mfma_f32_16x16x32_bf16 v[10:13], v[236:239], v[212:215], v[10:13]
	v_mfma_f32_16x16x32_bf16 v[14:17], v[240:243], v[212:215], v[14:17]
	v_mfma_f32_16x16x32_bf16 v[18:21], v[228:231], v[216:219], v[18:21]
	v_mfma_f32_16x16x32_bf16 v[22:25], v[232:235], v[216:219], v[22:25]
	v_mfma_f32_16x16x32_bf16 v[26:29], v[236:239], v[216:219], v[26:29]
	v_mfma_f32_16x16x32_bf16 v[30:33], v[240:243], v[216:219], v[30:33]
	v_mfma_f32_16x16x32_bf16 v[34:37], v[228:231], v[220:223], v[34:37]
	v_mfma_f32_16x16x32_bf16 v[38:41], v[232:235], v[220:223], v[38:41]
	v_mfma_f32_16x16x32_bf16 v[42:45], v[236:239], v[220:223], v[42:45]
	v_mfma_f32_16x16x32_bf16 v[46:49], v[240:243], v[220:223], v[46:49]
	v_mfma_f32_16x16x32_bf16 v[50:53], v[228:231], v[224:227], v[50:53]
	v_mfma_f32_16x16x32_bf16 v[54:57], v[232:235], v[224:227], v[54:57]
	v_mfma_f32_16x16x32_bf16 v[58:61], v[236:239], v[224:227], v[58:61]
	v_mfma_f32_16x16x32_bf16 v[62:65], v[240:243], v[224:227], v[62:65]
	s_barrier
	v_add_u32_e32 v204, 0x18000, v200
	v_add_u32_e32 v205, 0x18000, v202
	ds_read_b128 v[130:133], v204 offset:0
	ds_read_b128 v[134:137], v204 offset:2048
	ds_read_b128 v[138:141], v204 offset:4096
	ds_read_b128 v[142:145], v204 offset:6144
	ds_read_b128 v[146:149], v205 offset:0
	ds_read_b128 v[150:153], v205 offset:2048
	ds_read_b128 v[154:157], v205 offset:4096
	ds_read_b128 v[158:161], v205 offset:6144
	v_add_u32_e32 v204, 0x18000, v201
	v_add_u32_e32 v205, 0x18000, v203
	ds_read_b128 v[212:215], v204 offset:0
	ds_read_b128 v[216:219], v204 offset:2048
	ds_read_b128 v[220:223], v204 offset:4096
	ds_read_b128 v[224:227], v204 offset:6144
	ds_read_b128 v[228:231], v205 offset:0
	ds_read_b128 v[232:235], v205 offset:2048
	ds_read_b128 v[236:239], v205 offset:4096
	ds_read_b128 v[240:243], v205 offset:6144
	s_add_u32 m0, s76, 0xc000
	s_nop 0
	global_load_lds_dwordx4 v196, s[68:69]
	s_add_u32 m0, s76, 0xe000
	s_nop 0
	global_load_lds_dwordx4 v197, s[68:69]
	s_add_u32 m0, s76, 0x10000
	s_nop 0
	global_load_lds_dwordx4 v198, s[68:69]
	s_add_u32 m0, s76, 0x12000
	s_nop 0
	global_load_lds_dwordx4 v199, s[68:69]
	s_add_u32 m0, s76, 0x14000
	s_nop 0
	global_load_lds_dwordx4 v196, s[70:71]
	s_add_u32 m0, s76, 0x16000
	s_nop 0
	global_load_lds_dwordx4 v197, s[70:71]
	s_add_u32 s68, s68, 0x80
	s_addc_u32 s69, s69, 0
	s_add_u32 s70, s70, 0x80
	s_addc_u32 s71, s71, 0
	global_load_dwordx2 v[106:107], v208, s[74:75] offset:64
	global_load_dwordx2 v[110:111], v208, s[74:75] offset:96
	global_load_dwordx2 v[114:115], v209, s[74:75] offset:0
	global_load_dwordx2 v[118:119], v209, s[74:75] offset:32
	global_load_dwordx2 v[122:123], v209, s[74:75] offset:64
	global_load_dwordx2 v[126:127], v209, s[74:75] offset:96
	s_waitcnt vmcnt(19)
	s_waitcnt lgkmcnt(0)
	s_barrier
	v_mfma_f32_16x16x32_bf16 v[2:5], v[146:149], v[130:133], v[2:5]
	v_mfma_f32_16x16x32_bf16 v[6:9], v[150:153], v[130:133], v[6:9]
	v_mfma_f32_16x16x32_bf16 v[10:13], v[154:157], v[130:133], v[10:13]
	v_mfma_f32_16x16x32_bf16 v[14:17], v[158:161], v[130:133], v[14:17]
	v_mfma_f32_16x16x32_bf16 v[18:21], v[146:149], v[134:137], v[18:21]
	v_mfma_f32_16x16x32_bf16 v[22:25], v[150:153], v[134:137], v[22:25]
	v_mfma_f32_16x16x32_bf16 v[26:29], v[154:157], v[134:137], v[26:29]
	v_mfma_f32_16x16x32_bf16 v[30:33], v[158:161], v[134:137], v[30:33]
	v_mfma_f32_16x16x32_bf16 v[34:37], v[146:149], v[138:141], v[34:37]
	v_mfma_f32_16x16x32_bf16 v[38:41], v[150:153], v[138:141], v[38:41]
	v_mfma_f32_16x16x32_bf16 v[42:45], v[154:157], v[138:141], v[42:45]
	v_mfma_f32_16x16x32_bf16 v[46:49], v[158:161], v[138:141], v[46:49]
	v_mfma_f32_16x16x32_bf16 v[50:53], v[146:149], v[142:145], v[50:53]
	v_mfma_f32_16x16x32_bf16 v[54:57], v[150:153], v[142:145], v[54:57]
	v_mfma_f32_16x16x32_bf16 v[58:61], v[154:157], v[142:145], v[58:61]
	v_mfma_f32_16x16x32_bf16 v[62:65], v[158:161], v[142:145], v[62:65]
	v_mfma_f32_16x16x32_bf16 v[2:5], v[228:231], v[212:215], v[2:5]
	v_mfma_f32_16x16x32_bf16 v[6:9], v[232:235], v[212:215], v[6:9]
	v_mfma_f32_16x16x32_bf16 v[10:13], v[236:239], v[212:215], v[10:13]
	v_mfma_f32_16x16x32_bf16 v[14:17], v[240:243], v[212:215], v[14:17]
	v_mfma_f32_16x16x32_bf16 v[18:21], v[228:231], v[216:219], v[18:21]
	v_mfma_f32_16x16x32_bf16 v[22:25], v[232:235], v[216:219], v[22:25]
	v_mfma_f32_16x16x32_bf16 v[26:29], v[236:239], v[216:219], v[26:29]
	v_mfma_f32_16x16x32_bf16 v[30:33], v[240:243], v[216:219], v[30:33]
	v_mfma_f32_16x16x32_bf16 v[34:37], v[228:231], v[220:223], v[34:37]
	v_mfma_f32_16x16x32_bf16 v[38:41], v[232:235], v[220:223], v[38:41]
	v_mfma_f32_16x16x32_bf16 v[42:45], v[236:239], v[220:223], v[42:45]
	v_mfma_f32_16x16x32_bf16 v[46:49], v[240:243], v[220:223], v[46:49]
	v_mfma_f32_16x16x32_bf16 v[50:53], v[228:231], v[224:227], v[50:53]
	v_mfma_f32_16x16x32_bf16 v[54:57], v[232:235], v[224:227], v[54:57]
	v_mfma_f32_16x16x32_bf16 v[58:61], v[236:239], v[224:227], v[58:61]
	v_mfma_f32_16x16x32_bf16 v[62:65], v[240:243], v[224:227], v[62:65]
	s_barrier
	v_add_u32_e32 v204, 0x0, v200
	v_add_u32_e32 v205, 0x0, v202
	ds_read_b128 v[130:133], v204 offset:0
	ds_read_b128 v[134:137], v204 offset:2048
	ds_read_b128 v[138:141], v204 offset:4096
	ds_read_b128 v[142:145], v204 offset:6144
	ds_read_b128 v[146:149], v205 offset:0
	ds_read_b128 v[150:153], v205 offset:2048
	ds_read_b128 v[154:157], v205 offset:4096
	ds_read_b128 v[158:161], v205 offset:6144
	v_add_u32_e32 v204, 0x0, v201
	v_add_u32_e32 v205, 0x0, v203
	ds_read_b128 v[212:215], v204 offset:0
	ds_read_b128 v[216:219], v204 offset:2048
	ds_read_b128 v[220:223], v204 offset:4096
	ds_read_b128 v[224:227], v204 offset:6144
	ds_read_b128 v[228:231], v205 offset:0
	ds_read_b128 v[232:235], v205 offset:2048
	ds_read_b128 v[236:239], v205 offset:4096
	ds_read_b128 v[240:243], v205 offset:6144
	s_add_u32 m0, s76, 0x18000
	s_nop 0
	global_load_lds_dwordx4 v196, s[68:69]
	s_add_u32 m0, s76, 0x1a000
	s_nop 0
	global_load_lds_dwordx4 v197, s[68:69]
	s_add_u32 m0, s76, 0x1c000
	s_nop 0
	global_load_lds_dwordx4 v198, s[68:69]
	s_add_u32 m0, s76, 0x1e000
	s_nop 0
	global_load_lds_dwordx4 v199, s[68:69]
	s_add_u32 m0, s76, 0x20000
	s_nop 0
	global_load_lds_dwordx4 v196, s[70:71]
	s_add_u32 m0, s76, 0x22000
	s_nop 0
	global_load_lds_dwordx4 v197, s[70:71]
	s_add_u32 s68, s68, 0x80
	s_addc_u32 s69, s69, 0
	s_add_u32 s70, s70, 0x80
	s_addc_u32 s71, s71, 0
	s_waitcnt vmcnt(12)
	s_waitcnt lgkmcnt(0)
	s_barrier
	v_mfma_f32_16x16x32_bf16 v[2:5], v[146:149], v[130:133], v[2:5]
	v_mfma_f32_16x16x32_bf16 v[6:9], v[150:153], v[130:133], v[6:9]
	v_mfma_f32_16x16x32_bf16 v[10:13], v[154:157], v[130:133], v[10:13]
	v_mfma_f32_16x16x32_bf16 v[14:17], v[158:161], v[130:133], v[14:17]
	v_mfma_f32_16x16x32_bf16 v[18:21], v[146:149], v[134:137], v[18:21]
	v_mfma_f32_16x16x32_bf16 v[22:25], v[150:153], v[134:137], v[22:25]
	v_mfma_f32_16x16x32_bf16 v[26:29], v[154:157], v[134:137], v[26:29]
	v_mfma_f32_16x16x32_bf16 v[30:33], v[158:161], v[134:137], v[30:33]
	v_mfma_f32_16x16x32_bf16 v[34:37], v[146:149], v[138:141], v[34:37]
	v_mfma_f32_16x16x32_bf16 v[38:41], v[150:153], v[138:141], v[38:41]
	v_mfma_f32_16x16x32_bf16 v[42:45], v[154:157], v[138:141], v[42:45]
	v_mfma_f32_16x16x32_bf16 v[46:49], v[158:161], v[138:141], v[46:49]
	v_mfma_f32_16x16x32_bf16 v[50:53], v[146:149], v[142:145], v[50:53]
	v_mfma_f32_16x16x32_bf16 v[54:57], v[150:153], v[142:145], v[54:57]
	v_mfma_f32_16x16x32_bf16 v[58:61], v[154:157], v[142:145], v[58:61]
	v_mfma_f32_16x16x32_bf16 v[62:65], v[158:161], v[142:145], v[62:65]
	v_mfma_f32_16x16x32_bf16 v[2:5], v[228:231], v[212:215], v[2:5]
	v_mfma_f32_16x16x32_bf16 v[6:9], v[232:235], v[212:215], v[6:9]
	v_mfma_f32_16x16x32_bf16 v[10:13], v[236:239], v[212:215], v[10:13]
	v_mfma_f32_16x16x32_bf16 v[14:17], v[240:243], v[212:215], v[14:17]
	v_mfma_f32_16x16x32_bf16 v[18:21], v[228:231], v[216:219], v[18:21]
	v_mfma_f32_16x16x32_bf16 v[22:25], v[232:235], v[216:219], v[22:25]
	v_mfma_f32_16x16x32_bf16 v[26:29], v[236:239], v[216:219], v[26:29]
	v_mfma_f32_16x16x32_bf16 v[30:33], v[240:243], v[216:219], v[30:33]
	v_mfma_f32_16x16x32_bf16 v[34:37], v[228:231], v[220:223], v[34:37]
	v_mfma_f32_16x16x32_bf16 v[38:41], v[232:235], v[220:223], v[38:41]
	v_mfma_f32_16x16x32_bf16 v[42:45], v[236:239], v[220:223], v[42:45]
	v_mfma_f32_16x16x32_bf16 v[46:49], v[240:243], v[220:223], v[46:49]
	v_mfma_f32_16x16x32_bf16 v[50:53], v[228:231], v[224:227], v[50:53]
	v_mfma_f32_16x16x32_bf16 v[54:57], v[232:235], v[224:227], v[54:57]
	v_mfma_f32_16x16x32_bf16 v[58:61], v[236:239], v[224:227], v[58:61]
	v_mfma_f32_16x16x32_bf16 v[62:65], v[240:243], v[224:227], v[62:65]
	s_barrier
	v_add_u32_e32 v204, 0xc000, v200
	v_add_u32_e32 v205, 0xc000, v202
	ds_read_b128 v[130:133], v204 offset:0
	ds_read_b128 v[134:137], v204 offset:2048
	ds_read_b128 v[138:141], v204 offset:4096
	ds_read_b128 v[142:145], v204 offset:6144
	ds_read_b128 v[146:149], v205 offset:0
	ds_read_b128 v[150:153], v205 offset:2048
	ds_read_b128 v[154:157], v205 offset:4096
	ds_read_b128 v[158:161], v205 offset:6144
	v_add_u32_e32 v204, 0xc000, v201
	v_add_u32_e32 v205, 0xc000, v203
	ds_read_b128 v[212:215], v204 offset:0
	ds_read_b128 v[216:219], v204 offset:2048
	ds_read_b128 v[220:223], v204 offset:4096
	ds_read_b128 v[224:227], v204 offset:6144
	ds_read_b128 v[228:231], v205 offset:0
	ds_read_b128 v[232:235], v205 offset:2048
	ds_read_b128 v[236:239], v205 offset:4096
	ds_read_b128 v[240:243], v205 offset:6144
	s_add_u32 m0, s76, 0x0
	s_nop 0
	global_load_lds_dwordx4 v196, s[68:69]
	s_add_u32 m0, s76, 0x2000
	s_nop 0
	global_load_lds_dwordx4 v197, s[68:69]
	s_add_u32 m0, s76, 0x4000
	s_nop 0
	global_load_lds_dwordx4 v198, s[68:69]
	s_add_u32 m0, s76, 0x6000
	s_nop 0
	global_load_lds_dwordx4 v199, s[68:69]
	s_add_u32 m0, s76, 0x8000
	s_nop 0
	global_load_lds_dwordx4 v196, s[70:71]
	s_add_u32 m0, s76, 0xa000
	s_nop 0
	global_load_lds_dwordx4 v197, s[70:71]
	s_add_u32 s68, s68, 0x80
	s_addc_u32 s69, s69, 0
	s_add_u32 s70, s70, 0x80
	s_addc_u32 s71, s71, 0
	s_waitcnt vmcnt(6)
	s_waitcnt lgkmcnt(0)
	s_barrier
	v_mfma_f32_16x16x32_bf16 v[2:5], v[146:149], v[130:133], v[2:5]
	v_mfma_f32_16x16x32_bf16 v[6:9], v[150:153], v[130:133], v[6:9]
	v_mfma_f32_16x16x32_bf16 v[10:13], v[154:157], v[130:133], v[10:13]
	v_mfma_f32_16x16x32_bf16 v[14:17], v[158:161], v[130:133], v[14:17]
	v_mfma_f32_16x16x32_bf16 v[18:21], v[146:149], v[134:137], v[18:21]
	v_mfma_f32_16x16x32_bf16 v[22:25], v[150:153], v[134:137], v[22:25]
	v_mfma_f32_16x16x32_bf16 v[26:29], v[154:157], v[134:137], v[26:29]
	v_mfma_f32_16x16x32_bf16 v[30:33], v[158:161], v[134:137], v[30:33]
	v_mfma_f32_16x16x32_bf16 v[34:37], v[146:149], v[138:141], v[34:37]
	v_mfma_f32_16x16x32_bf16 v[38:41], v[150:153], v[138:141], v[38:41]
	v_mfma_f32_16x16x32_bf16 v[42:45], v[154:157], v[138:141], v[42:45]
	v_mfma_f32_16x16x32_bf16 v[46:49], v[158:161], v[138:141], v[46:49]
	v_mfma_f32_16x16x32_bf16 v[50:53], v[146:149], v[142:145], v[50:53]
	v_mfma_f32_16x16x32_bf16 v[54:57], v[150:153], v[142:145], v[54:57]
	v_mfma_f32_16x16x32_bf16 v[58:61], v[154:157], v[142:145], v[58:61]
	v_mfma_f32_16x16x32_bf16 v[62:65], v[158:161], v[142:145], v[62:65]
	v_mfma_f32_16x16x32_bf16 v[2:5], v[228:231], v[212:215], v[2:5]
	v_mfma_f32_16x16x32_bf16 v[6:9], v[232:235], v[212:215], v[6:9]
	v_mfma_f32_16x16x32_bf16 v[10:13], v[236:239], v[212:215], v[10:13]
	v_mfma_f32_16x16x32_bf16 v[14:17], v[240:243], v[212:215], v[14:17]
	v_mfma_f32_16x16x32_bf16 v[18:21], v[228:231], v[216:219], v[18:21]
	v_mfma_f32_16x16x32_bf16 v[22:25], v[232:235], v[216:219], v[22:25]
	v_mfma_f32_16x16x32_bf16 v[26:29], v[236:239], v[216:219], v[26:29]
	v_mfma_f32_16x16x32_bf16 v[30:33], v[240:243], v[216:219], v[30:33]
	v_mfma_f32_16x16x32_bf16 v[34:37], v[228:231], v[220:223], v[34:37]
	v_mfma_f32_16x16x32_bf16 v[38:41], v[232:235], v[220:223], v[38:41]
	v_mfma_f32_16x16x32_bf16 v[42:45], v[236:239], v[220:223], v[42:45]
	v_mfma_f32_16x16x32_bf16 v[46:49], v[240:243], v[220:223], v[46:49]
	v_mfma_f32_16x16x32_bf16 v[50:53], v[228:231], v[224:227], v[50:53]
	v_mfma_f32_16x16x32_bf16 v[54:57], v[232:235], v[224:227], v[54:57]
	v_mfma_f32_16x16x32_bf16 v[58:61], v[236:239], v[224:227], v[58:61]
	v_mfma_f32_16x16x32_bf16 v[62:65], v[240:243], v[224:227], v[62:65]
	s_barrier
	s_mov_b32 s16, 12
.Ldn_kloop2:
	v_add_u32_e32 v204, 0x18000, v200
	v_add_u32_e32 v205, 0x18000, v202
	ds_read_b128 v[130:133], v204 offset:0
	ds_read_b128 v[134:137], v204 offset:2048
	ds_read_b128 v[138:141], v204 offset:4096
	ds_read_b128 v[142:145], v204 offset:6144
	ds_read_b128 v[146:149], v205 offset:0
	ds_read_b128 v[150:153], v205 offset:2048
	ds_read_b128 v[154:157], v205 offset:4096
	ds_read_b128 v[158:161], v205 offset:6144
	v_add_u32_e32 v204, 0x18000, v201
	v_add_u32_e32 v205, 0x18000, v203
	ds_read_b128 v[212:215], v204 offset:0
	ds_read_b128 v[216:219], v204 offset:2048
	ds_read_b128 v[220:223], v204 offset:4096
	ds_read_b128 v[224:227], v204 offset:6144
	ds_read_b128 v[228:231], v205 offset:0
	ds_read_b128 v[232:235], v205 offset:2048
	ds_read_b128 v[236:239], v205 offset:4096
	ds_read_b128 v[240:243], v205 offset:6144
	s_add_u32 m0, s76, 0xc000
	s_nop 0
	global_load_lds_dwordx4 v196, s[68:69]
	s_add_u32 m0, s76, 0xe000
	s_nop 0
	global_load_lds_dwordx4 v197, s[68:69]
	s_add_u32 m0, s76, 0x10000
	s_nop 0
	global_load_lds_dwordx4 v198, s[68:69]
	s_add_u32 m0, s76, 0x12000
	s_nop 0
	global_load_lds_dwordx4 v199, s[68:69]
	s_add_u32 m0, s76, 0x14000
	s_nop 0
	global_load_lds_dwordx4 v196, s[70:71]
	s_add_u32 m0, s76, 0x16000
	s_nop 0
	global_load_lds_dwordx4 v197, s[70:71]
	s_add_u32 s68, s68, 0x80
	s_addc_u32 s69, s69, 0
	s_add_u32 s70, s70, 0x80
	s_addc_u32 s71, s71, 0
	s_waitcnt vmcnt(6)
	s_waitcnt lgkmcnt(0)
	s_barrier
	v_mfma_f32_16x16x32_bf16 v[2:5], v[146:149], v[130:133], v[2:5]
	v_mfma_f32_16x16x32_bf16 v[6:9], v[150:153], v[130:133], v[6:9]
	v_mfma_f32_16x16x32_bf16 v[10:13], v[154:157], v[130:133], v[10:13]
	v_mfma_f32_16x16x32_bf16 v[14:17], v[158:161], v[130:133], v[14:17]
	v_mfma_f32_16x16x32_bf16 v[18:21], v[146:149], v[134:137], v[18:21]
	v_mfma_f32_16x16x32_bf16 v[22:25], v[150:153], v[134:137], v[22:25]
	v_mfma_f32_16x16x32_bf16 v[26:29], v[154:157], v[134:137], v[26:29]
	v_mfma_f32_16x16x32_bf16 v[30:33], v[158:161], v[134:137], v[30:33]
	v_mfma_f32_16x16x32_bf16 v[34:37], v[146:149], v[138:141], v[34:37]
	v_mfma_f32_16x16x32_bf16 v[38:41], v[150:153], v[138:141], v[38:41]
	v_mfma_f32_16x16x32_bf16 v[42:45], v[154:157], v[138:141], v[42:45]
	v_mfma_f32_16x16x32_bf16 v[46:49], v[158:161], v[138:141], v[46:49]
	v_mfma_f32_16x16x32_bf16 v[50:53], v[146:149], v[142:145], v[50:53]
	v_mfma_f32_16x16x32_bf16 v[54:57], v[150:153], v[142:145], v[54:57]
	v_mfma_f32_16x16x32_bf16 v[58:61], v[154:157], v[142:145], v[58:61]
	v_mfma_f32_16x16x32_bf16 v[62:65], v[158:161], v[142:145], v[62:65]
	v_mfma_f32_16x16x32_bf16 v[2:5], v[228:231], v[212:215], v[2:5]
	v_mfma_f32_16x16x32_bf16 v[6:9], v[232:235], v[212:215], v[6:9]
	v_mfma_f32_16x16x32_bf16 v[10:13], v[236:239], v[212:215], v[10:13]
	v_mfma_f32_16x16x32_bf16 v[14:17], v[240:243], v[212:215], v[14:17]
	v_mfma_f32_16x16x32_bf16 v[18:21], v[228:231], v[216:219], v[18:21]
	v_mfma_f32_16x16x32_bf16 v[22:25], v[232:235], v[216:219], v[22:25]
	v_mfma_f32_16x16x32_bf16 v[26:29], v[236:239], v[216:219], v[26:29]
	v_mfma_f32_16x16x32_bf16 v[30:33], v[240:243], v[216:219], v[30:33]
	v_mfma_f32_16x16x32_bf16 v[34:37], v[228:231], v[220:223], v[34:37]
	v_mfma_f32_16x16x32_bf16 v[38:41], v[232:235], v[220:223], v[38:41]
	v_mfma_f32_16x16x32_bf16 v[42:45], v[236:239], v[220:223], v[42:45]
	v_mfma_f32_16x16x32_bf16 v[46:49], v[240:243], v[220:223], v[46:49]
	v_mfma_f32_16x16x32_bf16 v[50:53], v[228:231], v[224:227], v[50:53]
	v_mfma_f32_16x16x32_bf16 v[54:57], v[232:235], v[224:227], v[54:57]
	v_mfma_f32_16x16x32_bf16 v[58:61], v[236:239], v[224:227], v[58:61]
	v_mfma_f32_16x16x32_bf16 v[62:65], v[240:243], v[224:227], v[62:65]
	s_barrier
	v_add_u32_e32 v204, 0x0, v200
	v_add_u32_e32 v205, 0x0, v202
	ds_read_b128 v[130:133], v204 offset:0
	ds_read_b128 v[134:137], v204 offset:2048
	ds_read_b128 v[138:141], v204 offset:4096
	ds_read_b128 v[142:145], v204 offset:6144
	ds_read_b128 v[146:149], v205 offset:0
	ds_read_b128 v[150:153], v205 offset:2048
	ds_read_b128 v[154:157], v205 offset:4096
	ds_read_b128 v[158:161], v205 offset:6144
	v_add_u32_e32 v204, 0x0, v201
	v_add_u32_e32 v205, 0x0, v203
	ds_read_b128 v[212:215], v204 offset:0
	ds_read_b128 v[216:219], v204 offset:2048
	ds_read_b128 v[220:223], v204 offset:4096
	ds_read_b128 v[224:227], v204 offset:6144
	ds_read_b128 v[228:231], v205 offset:0
	ds_read_b128 v[232:235], v205 offset:2048
	ds_read_b128 v[236:239], v205 offset:4096
	ds_read_b128 v[240:243], v205 offset:6144
	s_add_u32 m0, s76, 0x18000
	s_nop 0
	global_load_lds_dwordx4 v196, s[68:69]
	s_add_u32 m0, s76, 0x1a000
	s_nop 0
	global_load_lds_dwordx4 v197, s[68:69]
	s_add_u32 m0, s76, 0x1c000
	s_nop 0
	global_load_lds_dwordx4 v198, s[68:69]
	s_add_u32 m0, s76, 0x1e000
	s_nop 0
	global_load_lds_dwordx4 v199, s[68:69]
	s_add_u32 m0, s76, 0x20000
	s_nop 0
	global_load_lds_dwordx4 v196, s[70:71]
	s_add_u32 m0, s76, 0x22000
	s_nop 0
	global_load_lds_dwordx4 v197, s[70:71]
	s_add_u32 s68, s68, 0x80
	s_addc_u32 s69, s69, 0
	s_add_u32 s70, s70, 0x80
	s_addc_u32 s71, s71, 0
	s_waitcnt vmcnt(6)
	s_waitcnt lgkmcnt(0)
	s_barrier
	v_mfma_f32_16x16x32_bf16 v[2:5], v[146:149], v[130:133], v[2:5]
	v_mfma_f32_16x16x32_bf16 v[6:9], v[150:153], v[130:133], v[6:9]
	v_mfma_f32_16x16x32_bf16 v[10:13], v[154:157], v[130:133], v[10:13]
	v_mfma_f32_16x16x32_bf16 v[14:17], v[158:161], v[130:133], v[14:17]
	v_mfma_f32_16x16x32_bf16 v[18:21], v[146:149], v[134:137], v[18:21]
	v_mfma_f32_16x16x32_bf16 v[22:25], v[150:153], v[134:137], v[22:25]
	v_mfma_f32_16x16x32_bf16 v[26:29], v[154:157], v[134:137], v[26:29]
	v_mfma_f32_16x16x32_bf16 v[30:33], v[158:161], v[134:137], v[30:33]
	v_mfma_f32_16x16x32_bf16 v[34:37], v[146:149], v[138:141], v[34:37]
	v_mfma_f32_16x16x32_bf16 v[38:41], v[150:153], v[138:141], v[38:41]
	v_mfma_f32_16x16x32_bf16 v[42:45], v[154:157], v[138:141], v[42:45]
	v_mfma_f32_16x16x32_bf16 v[46:49], v[158:161], v[138:141], v[46:49]
	v_mfma_f32_16x16x32_bf16 v[50:53], v[146:149], v[142:145], v[50:53]
	v_mfma_f32_16x16x32_bf16 v[54:57], v[150:153], v[142:145], v[54:57]
	v_mfma_f32_16x16x32_bf16 v[58:61], v[154:157], v[142:145], v[58:61]
	v_mfma_f32_16x16x32_bf16 v[62:65], v[158:161], v[142:145], v[62:65]
	v_mfma_f32_16x16x32_bf16 v[2:5], v[228:231], v[212:215], v[2:5]
	v_mfma_f32_16x16x32_bf16 v[6:9], v[232:235], v[212:215], v[6:9]
	v_mfma_f32_16x16x32_bf16 v[10:13], v[236:239], v[212:215], v[10:13]
	v_mfma_f32_16x16x32_bf16 v[14:17], v[240:243], v[212:215], v[14:17]
	v_mfma_f32_16x16x32_bf16 v[18:21], v[228:231], v[216:219], v[18:21]
	v_mfma_f32_16x16x32_bf16 v[22:25], v[232:235], v[216:219], v[22:25]
	v_mfma_f32_16x16x32_bf16 v[26:29], v[236:239], v[216:219], v[26:29]
	v_mfma_f32_16x16x32_bf16 v[30:33], v[240:243], v[216:219], v[30:33]
	v_mfma_f32_16x16x32_bf16 v[34:37], v[228:231], v[220:223], v[34:37]
	v_mfma_f32_16x16x32_bf16 v[38:41], v[232:235], v[220:223], v[38:41]
	v_mfma_f32_16x16x32_bf16 v[42:45], v[236:239], v[220:223], v[42:45]
	v_mfma_f32_16x16x32_bf16 v[46:49], v[240:243], v[220:223], v[46:49]
	v_mfma_f32_16x16x32_bf16 v[50:53], v[228:231], v[224:227], v[50:53]
	v_mfma_f32_16x16x32_bf16 v[54:57], v[232:235], v[224:227], v[54:57]
	v_mfma_f32_16x16x32_bf16 v[58:61], v[236:239], v[224:227], v[58:61]
	v_mfma_f32_16x16x32_bf16 v[62:65], v[240:243], v[224:227], v[62:65]
	s_barrier
	v_add_u32_e32 v204, 0xc000, v200
	v_add_u32_e32 v205, 0xc000, v202
	ds_read_b128 v[130:133], v204 offset:0
	ds_read_b128 v[134:137], v204 offset:2048
	ds_read_b128 v[138:141], v204 offset:4096
	ds_read_b128 v[142:145], v204 offset:6144
	ds_read_b128 v[146:149], v205 offset:0
	ds_read_b128 v[150:153], v205 offset:2048
	ds_read_b128 v[154:157], v205 offset:4096
	ds_read_b128 v[158:161], v205 offset:6144
	v_add_u32_e32 v204, 0xc000, v201
	v_add_u32_e32 v205, 0xc000, v203
	ds_read_b128 v[212:215], v204 offset:0
	ds_read_b128 v[216:219], v204 offset:2048
	ds_read_b128 v[220:223], v204 offset:4096
	ds_read_b128 v[224:227], v204 offset:6144
	ds_read_b128 v[228:231], v205 offset:0
	ds_read_b128 v[232:235], v205 offset:2048
	ds_read_b128 v[236:239], v205 offset:4096
	ds_read_b128 v[240:243], v205 offset:6144
	s_add_u32 m0, s76, 0x0
	s_nop 0
	global_load_lds_dwordx4 v196, s[68:69]
	s_add_u32 m0, s76, 0x2000
	s_nop 0
	global_load_lds_dwordx4 v197, s[68:69]
	s_add_u32 m0, s76, 0x4000
	s_nop 0
	global_load_lds_dwordx4 v198, s[68:69]
	s_add_u32 m0, s76, 0x6000
	s_nop 0
	global_load_lds_dwordx4 v199, s[68:69]
	s_add_u32 m0, s76, 0x8000
	s_nop 0
	global_load_lds_dwordx4 v196, s[70:71]
	s_add_u32 m0, s76, 0xa000
	s_nop 0
	global_load_lds_dwordx4 v197, s[70:71]
	s_add_u32 s68, s68, 0x80
	s_addc_u32 s69, s69, 0
	s_add_u32 s70, s70, 0x80
	s_addc_u32 s71, s71, 0
	s_waitcnt vmcnt(6)
	s_waitcnt lgkmcnt(0)
	s_barrier
	v_mfma_f32_16x16x32_bf16 v[2:5], v[146:149], v[130:133], v[2:5]
	v_mfma_f32_16x16x32_bf16 v[6:9], v[150:153], v[130:133], v[6:9]
	v_mfma_f32_16x16x32_bf16 v[10:13], v[154:157], v[130:133], v[10:13]
	v_mfma_f32_16x16x32_bf16 v[14:17], v[158:161], v[130:133], v[14:17]
	v_mfma_f32_16x16x32_bf16 v[18:21], v[146:149], v[134:137], v[18:21]
	v_mfma_f32_16x16x32_bf16 v[22:25], v[150:153], v[134:137], v[22:25]
	v_mfma_f32_16x16x32_bf16 v[26:29], v[154:157], v[134:137], v[26:29]
	v_mfma_f32_16x16x32_bf16 v[30:33], v[158:161], v[134:137], v[30:33]
	v_mfma_f32_16x16x32_bf16 v[34:37], v[146:149], v[138:141], v[34:37]
	v_mfma_f32_16x16x32_bf16 v[38:41], v[150:153], v[138:141], v[38:41]
	v_mfma_f32_16x16x32_bf16 v[42:45], v[154:157], v[138:141], v[42:45]
	v_mfma_f32_16x16x32_bf16 v[46:49], v[158:161], v[138:141], v[46:49]
	v_mfma_f32_16x16x32_bf16 v[50:53], v[146:149], v[142:145], v[50:53]
	v_mfma_f32_16x16x32_bf16 v[54:57], v[150:153], v[142:145], v[54:57]
	v_mfma_f32_16x16x32_bf16 v[58:61], v[154:157], v[142:145], v[58:61]
	v_mfma_f32_16x16x32_bf16 v[62:65], v[158:161], v[142:145], v[62:65]
	v_mfma_f32_16x16x32_bf16 v[2:5], v[228:231], v[212:215], v[2:5]
	v_mfma_f32_16x16x32_bf16 v[6:9], v[232:235], v[212:215], v[6:9]
	v_mfma_f32_16x16x32_bf16 v[10:13], v[236:239], v[212:215], v[10:13]
	v_mfma_f32_16x16x32_bf16 v[14:17], v[240:243], v[212:215], v[14:17]
	v_mfma_f32_16x16x32_bf16 v[18:21], v[228:231], v[216:219], v[18:21]
	v_mfma_f32_16x16x32_bf16 v[22:25], v[232:235], v[216:219], v[22:25]
	v_mfma_f32_16x16x32_bf16 v[26:29], v[236:239], v[216:219], v[26:29]
	v_mfma_f32_16x16x32_bf16 v[30:33], v[240:243], v[216:219], v[30:33]
	v_mfma_f32_16x16x32_bf16 v[34:37], v[228:231], v[220:223], v[34:37]
	v_mfma_f32_16x16x32_bf16 v[38:41], v[232:235], v[220:223], v[38:41]
	v_mfma_f32_16x16x32_bf16 v[42:45], v[236:239], v[220:223], v[42:45]
	v_mfma_f32_16x16x32_bf16 v[46:49], v[240:243], v[220:223], v[46:49]
	v_mfma_f32_16x16x32_bf16 v[50:53], v[228:231], v[224:227], v[50:53]
	v_mfma_f32_16x16x32_bf16 v[54:57], v[232:235], v[224:227], v[54:57]
	v_mfma_f32_16x16x32_bf16 v[58:61], v[236:239], v[224:227], v[58:61]
	v_mfma_f32_16x16x32_bf16 v[62:65], v[240:243], v[224:227], v[62:65]
	s_barrier
	s_add_i32 s16, s16, -1
	s_cmp_lg_u32 s16, 0
	s_cbranch_scc1 .Ldn_kloop2
	v_add_u32_e32 v204, 0x18000, v200
	v_add_u32_e32 v205, 0x18000, v202
	ds_read_b128 v[130:133], v204 offset:0
	ds_read_b128 v[134:137], v204 offset:2048
	ds_read_b128 v[138:141], v204 offset:4096
	ds_read_b128 v[142:145], v204 offset:6144
	ds_read_b128 v[146:149], v205 offset:0
	ds_read_b128 v[150:153], v205 offset:2048
	ds_read_b128 v[154:157], v205 offset:4096
	ds_read_b128 v[158:161], v205 offset:6144
	v_add_u32_e32 v204, 0x18000, v201
	v_add_u32_e32 v205, 0x18000, v203
	ds_read_b128 v[212:215], v204 offset:0
	ds_read_b128 v[216:219], v204 offset:2048
	ds_read_b128 v[220:223], v204 offset:4096
	ds_read_b128 v[224:227], v204 offset:6144
	ds_read_b128 v[228:231], v205 offset:0
	ds_read_b128 v[232:235], v205 offset:2048
	ds_read_b128 v[236:239], v205 offset:4096
	ds_read_b128 v[240:243], v205 offset:6144
	s_add_u32 m0, s76, 0xc000
	s_nop 0
	global_load_lds_dwordx4 v196, s[68:69]
	s_add_u32 m0, s76, 0xe000
	s_nop 0
	global_load_lds_dwordx4 v197, s[68:69]
	s_add_u32 m0, s76, 0x10000
	s_nop 0
	global_load_lds_dwordx4 v198, s[68:69]
	s_add_u32 m0, s76, 0x12000
	s_nop 0
	global_load_lds_dwordx4 v199, s[68:69]
	s_add_u32 m0, s76, 0x14000
	s_nop 0
	global_load_lds_dwordx4 v196, s[70:71]
	s_add_u32 m0, s76, 0x16000
	s_nop 0
	global_load_lds_dwordx4 v197, s[70:71]
	s_add_u32 s68, s68, 0x80
	s_addc_u32 s69, s69, 0
	s_add_u32 s70, s70, 0x80
	s_addc_u32 s71, s71, 0
	s_waitcnt vmcnt(6)
	s_waitcnt lgkmcnt(0)
	s_barrier
	v_mfma_f32_16x16x32_bf16 v[2:5], v[146:149], v[130:133], v[2:5]
	v_mfma_f32_16x16x32_bf16 v[6:9], v[150:153], v[130:133], v[6:9]
	v_mfma_f32_16x16x32_bf16 v[10:13], v[154:157], v[130:133], v[10:13]
	v_mfma_f32_16x16x32_bf16 v[14:17], v[158:161], v[130:133], v[14:17]
	v_mfma_f32_16x16x32_bf16 v[18:21], v[146:149], v[134:137], v[18:21]
	v_mfma_f32_16x16x32_bf16 v[22:25], v[150:153], v[134:137], v[22:25]
	v_mfma_f32_16x16x32_bf16 v[26:29], v[154:157], v[134:137], v[26:29]
	v_mfma_f32_16x16x32_bf16 v[30:33], v[158:161], v[134:137], v[30:33]
	v_mfma_f32_16x16x32_bf16 v[34:37], v[146:149], v[138:141], v[34:37]
	v_mfma_f32_16x16x32_bf16 v[38:41], v[150:153], v[138:141], v[38:41]
	v_mfma_f32_16x16x32_bf16 v[42:45], v[154:157], v[138:141], v[42:45]
	v_mfma_f32_16x16x32_bf16 v[46:49], v[158:161], v[138:141], v[46:49]
	v_mfma_f32_16x16x32_bf16 v[50:53], v[146:149], v[142:145], v[50:53]
	v_mfma_f32_16x16x32_bf16 v[54:57], v[150:153], v[142:145], v[54:57]
	v_mfma_f32_16x16x32_bf16 v[58:61], v[154:157], v[142:145], v[58:61]
	v_mfma_f32_16x16x32_bf16 v[62:65], v[158:161], v[142:145], v[62:65]
	v_mfma_f32_16x16x32_bf16 v[2:5], v[228:231], v[212:215], v[2:5]
	v_mfma_f32_16x16x32_bf16 v[6:9], v[232:235], v[212:215], v[6:9]
	v_mfma_f32_16x16x32_bf16 v[10:13], v[236:239], v[212:215], v[10:13]
	v_mfma_f32_16x16x32_bf16 v[14:17], v[240:243], v[212:215], v[14:17]
	v_mfma_f32_16x16x32_bf16 v[18:21], v[228:231], v[216:219], v[18:21]
	v_mfma_f32_16x16x32_bf16 v[22:25], v[232:235], v[216:219], v[22:25]
	v_mfma_f32_16x16x32_bf16 v[26:29], v[236:239], v[216:219], v[26:29]
	v_mfma_f32_16x16x32_bf16 v[30:33], v[240:243], v[216:219], v[30:33]
	v_mfma_f32_16x16x32_bf16 v[34:37], v[228:231], v[220:223], v[34:37]
	v_mfma_f32_16x16x32_bf16 v[38:41], v[232:235], v[220:223], v[38:41]
	v_mfma_f32_16x16x32_bf16 v[42:45], v[236:239], v[220:223], v[42:45]
	v_mfma_f32_16x16x32_bf16 v[46:49], v[240:243], v[220:223], v[46:49]
	v_mfma_f32_16x16x32_bf16 v[50:53], v[228:231], v[224:227], v[50:53]
	v_mfma_f32_16x16x32_bf16 v[54:57], v[232:235], v[224:227], v[54:57]
	v_mfma_f32_16x16x32_bf16 v[58:61], v[236:239], v[224:227], v[58:61]
	v_mfma_f32_16x16x32_bf16 v[62:65], v[240:243], v[224:227], v[62:65]
	s_barrier
	v_add_u32_e32 v204, 0x0, v200
	v_add_u32_e32 v205, 0x0, v202
	ds_read_b128 v[130:133], v204 offset:0
	ds_read_b128 v[134:137], v204 offset:2048
	ds_read_b128 v[138:141], v204 offset:4096
	ds_read_b128 v[142:145], v204 offset:6144
	ds_read_b128 v[146:149], v205 offset:0
	ds_read_b128 v[150:153], v205 offset:2048
	ds_read_b128 v[154:157], v205 offset:4096
	ds_read_b128 v[158:161], v205 offset:6144
	v_add_u32_e32 v204, 0x0, v201
	v_add_u32_e32 v205, 0x0, v203
	ds_read_b128 v[212:215], v204 offset:0
	ds_read_b128 v[216:219], v204 offset:2048
	ds_read_b128 v[220:223], v204 offset:4096
	ds_read_b128 v[224:227], v204 offset:6144
	ds_read_b128 v[228:231], v205 offset:0
	ds_read_b128 v[232:235], v205 offset:2048
	ds_read_b128 v[236:239], v205 offset:4096
	ds_read_b128 v[240:243], v205 offset:6144
	s_waitcnt vmcnt(0)
	s_waitcnt lgkmcnt(0)
	s_barrier
	v_mfma_f32_16x16x32_bf16 v[2:5], v[146:149], v[130:133], v[2:5]
	v_mfma_f32_16x16x32_bf16 v[6:9], v[150:153], v[130:133], v[6:9]
	v_mfma_f32_16x16x32_bf16 v[10:13], v[154:157], v[130:133], v[10:13]
	v_mfma_f32_16x16x32_bf16 v[14:17], v[158:161], v[130:133], v[14:17]
	v_mfma_f32_16x16x32_bf16 v[18:21], v[146:149], v[134:137], v[18:21]
	v_mfma_f32_16x16x32_bf16 v[22:25], v[150:153], v[134:137], v[22:25]
	v_mfma_f32_16x16x32_bf16 v[26:29], v[154:157], v[134:137], v[26:29]
	v_mfma_f32_16x16x32_bf16 v[30:33], v[158:161], v[134:137], v[30:33]
	v_mfma_f32_16x16x32_bf16 v[34:37], v[146:149], v[138:141], v[34:37]
	v_mfma_f32_16x16x32_bf16 v[38:41], v[150:153], v[138:141], v[38:41]
	v_mfma_f32_16x16x32_bf16 v[42:45], v[154:157], v[138:141], v[42:45]
	v_mfma_f32_16x16x32_bf16 v[46:49], v[158:161], v[138:141], v[46:49]
	v_mfma_f32_16x16x32_bf16 v[50:53], v[146:149], v[142:145], v[50:53]
	v_mfma_f32_16x16x32_bf16 v[54:57], v[150:153], v[142:145], v[54:57]
	v_mfma_f32_16x16x32_bf16 v[58:61], v[154:157], v[142:145], v[58:61]
	v_mfma_f32_16x16x32_bf16 v[62:65], v[158:161], v[142:145], v[62:65]
	v_mfma_f32_16x16x32_bf16 v[2:5], v[228:231], v[212:215], v[2:5]
	v_mfma_f32_16x16x32_bf16 v[6:9], v[232:235], v[212:215], v[6:9]
	v_mfma_f32_16x16x32_bf16 v[10:13], v[236:239], v[212:215], v[10:13]
	v_mfma_f32_16x16x32_bf16 v[14:17], v[240:243], v[212:215], v[14:17]
	v_mfma_f32_16x16x32_bf16 v[18:21], v[228:231], v[216:219], v[18:21]
	v_mfma_f32_16x16x32_bf16 v[22:25], v[232:235], v[216:219], v[22:25]
	v_mfma_f32_16x16x32_bf16 v[26:29], v[236:239], v[216:219], v[26:29]
	v_mfma_f32_16x16x32_bf16 v[30:33], v[240:243], v[216:219], v[30:33]
	v_mfma_f32_16x16x32_bf16 v[34:37], v[228:231], v[220:223], v[34:37]
	v_mfma_f32_16x16x32_bf16 v[38:41], v[232:235], v[220:223], v[38:41]
	v_mfma_f32_16x16x32_bf16 v[42:45], v[236:239], v[220:223], v[42:45]
	v_mfma_f32_16x16x32_bf16 v[46:49], v[240:243], v[220:223], v[46:49]
	v_mfma_f32_16x16x32_bf16 v[50:53], v[228:231], v[224:227], v[50:53]
	v_mfma_f32_16x16x32_bf16 v[54:57], v[232:235], v[224:227], v[54:57]
	v_mfma_f32_16x16x32_bf16 v[58:61], v[236:239], v[224:227], v[58:61]
	v_mfma_f32_16x16x32_bf16 v[62:65], v[240:243], v[224:227], v[62:65]
	s_barrier
	v_add_u32_e32 v204, 0xc000, v200
	v_add_u32_e32 v205, 0xc000, v202
	ds_read_b128 v[130:133], v204 offset:0
	ds_read_b128 v[134:137], v204 offset:2048
	ds_read_b128 v[138:141], v204 offset:4096
	ds_read_b128 v[142:145], v204 offset:6144
	ds_read_b128 v[146:149], v205 offset:0
	ds_read_b128 v[150:153], v205 offset:2048
	ds_read_b128 v[154:157], v205 offset:4096
	ds_read_b128 v[158:161], v205 offset:6144
	v_add_u32_e32 v204, 0xc000, v201
	v_add_u32_e32 v205, 0xc000, v203
	ds_read_b128 v[212:215], v204 offset:0
	ds_read_b128 v[216:219], v204 offset:2048
	ds_read_b128 v[220:223], v204 offset:4096
	ds_read_b128 v[224:227], v204 offset:6144
	ds_read_b128 v[228:231], v205 offset:0
	ds_read_b128 v[232:235], v205 offset:2048
	ds_read_b128 v[236:239], v205 offset:4096
	ds_read_b128 v[240:243], v205 offset:6144
	s_waitcnt lgkmcnt(0)
	s_barrier
	v_mfma_f32_16x16x32_bf16 v[2:5], v[146:149], v[130:133], v[2:5]
	v_mfma_f32_16x16x32_bf16 v[6:9], v[150:153], v[130:133], v[6:9]
	v_mfma_f32_16x16x32_bf16 v[10:13], v[154:157], v[130:133], v[10:13]
	v_mfma_f32_16x16x32_bf16 v[14:17], v[158:161], v[130:133], v[14:17]
	v_mfma_f32_16x16x32_bf16 v[18:21], v[146:149], v[134:137], v[18:21]
	v_mfma_f32_16x16x32_bf16 v[22:25], v[150:153], v[134:137], v[22:25]
	v_mfma_f32_16x16x32_bf16 v[26:29], v[154:157], v[134:137], v[26:29]
	v_mfma_f32_16x16x32_bf16 v[30:33], v[158:161], v[134:137], v[30:33]
	v_mfma_f32_16x16x32_bf16 v[34:37], v[146:149], v[138:141], v[34:37]
	v_mfma_f32_16x16x32_bf16 v[38:41], v[150:153], v[138:141], v[38:41]
	v_mfma_f32_16x16x32_bf16 v[42:45], v[154:157], v[138:141], v[42:45]
	v_mfma_f32_16x16x32_bf16 v[46:49], v[158:161], v[138:141], v[46:49]
	v_mfma_f32_16x16x32_bf16 v[50:53], v[146:149], v[142:145], v[50:53]
	v_mfma_f32_16x16x32_bf16 v[54:57], v[150:153], v[142:145], v[54:57]
	v_mfma_f32_16x16x32_bf16 v[58:61], v[154:157], v[142:145], v[58:61]
	v_mfma_f32_16x16x32_bf16 v[62:65], v[158:161], v[142:145], v[62:65]
	v_mfma_f32_16x16x32_bf16 v[2:5], v[228:231], v[212:215], v[2:5]
	v_mfma_f32_16x16x32_bf16 v[6:9], v[232:235], v[212:215], v[6:9]
	v_mfma_f32_16x16x32_bf16 v[10:13], v[236:239], v[212:215], v[10:13]
	v_mfma_f32_16x16x32_bf16 v[14:17], v[240:243], v[212:215], v[14:17]
	v_mfma_f32_16x16x32_bf16 v[18:21], v[228:231], v[216:219], v[18:21]
	v_mfma_f32_16x16x32_bf16 v[22:25], v[232:235], v[216:219], v[22:25]
	v_mfma_f32_16x16x32_bf16 v[26:29], v[236:239], v[216:219], v[26:29]
	v_mfma_f32_16x16x32_bf16 v[30:33], v[240:243], v[216:219], v[30:33]
	v_mfma_f32_16x16x32_bf16 v[34:37], v[228:231], v[220:223], v[34:37]
	v_mfma_f32_16x16x32_bf16 v[38:41], v[232:235], v[220:223], v[38:41]
	v_mfma_f32_16x16x32_bf16 v[42:45], v[236:239], v[220:223], v[42:45]
	v_mfma_f32_16x16x32_bf16 v[46:49], v[240:243], v[220:223], v[46:49]
	v_mfma_f32_16x16x32_bf16 v[50:53], v[228:231], v[224:227], v[50:53]
	v_mfma_f32_16x16x32_bf16 v[54:57], v[232:235], v[224:227], v[54:57]
	v_mfma_f32_16x16x32_bf16 v[58:61], v[236:239], v[224:227], v[58:61]
	v_mfma_f32_16x16x32_bf16 v[62:65], v[240:243], v[224:227], v[62:65]
.Ldn_join:
	s_waitcnt vmcnt(0)
	s_nop 7
	v_lshlrev_b32_e32 v68, 16, v67
	v_and_b32_e32 v69, 0xffff0000, v67
	v_and_b32_e32 v67, 0xffff0000, v66
	v_lshlrev_b32_e32 v66, 16, v66
	v_pk_fma_f32 v[4:5], v[4:5], v[176:177], v[68:69]
	v_pk_fma_f32 v[2:3], v[2:3], v[174:175], v[66:67]
	s_nop 0
	v_cvt_pk_bf16_f32 v2, v2, v3
	v_cvt_pk_bf16_f32 v3, v4, v5
	global_store_dwordx2 v206, v[2:3], s[74:75] offset:0
	v_lshlrev_b32_e32 v72, 16, v71
	v_and_b32_e32 v73, 0xffff0000, v71
	v_and_b32_e32 v71, 0xffff0000, v70
	v_lshlrev_b32_e32 v70, 16, v70
	v_pk_fma_f32 v[8:9], v[8:9], v[180:181], v[72:73]
	v_pk_fma_f32 v[6:7], v[6:7], v[178:179], v[70:71]
	s_nop 0
	v_cvt_pk_bf16_f32 v6, v6, v7
	v_cvt_pk_bf16_f32 v7, v8, v9
	global_store_dwordx2 v206, v[6:7], s[74:75] offset:32
	v_lshlrev_b32_e32 v76, 16, v75
	v_and_b32_e32 v77, 0xffff0000, v75
	v_and_b32_e32 v75, 0xffff0000, v74
	v_lshlrev_b32_e32 v74, 16, v74
	v_pk_fma_f32 v[12:13], v[12:13], v[184:185], v[76:77]
	v_pk_fma_f32 v[10:11], v[10:11], v[182:183], v[74:75]
	s_nop 0
	v_cvt_pk_bf16_f32 v10, v10, v11
	v_cvt_pk_bf16_f32 v11, v12, v13
	global_store_dwordx2 v206, v[10:11], s[74:75] offset:64
	v_lshlrev_b32_e32 v80, 16, v79
	v_and_b32_e32 v81, 0xffff0000, v79
	v_and_b32_e32 v79, 0xffff0000, v78
	v_lshlrev_b32_e32 v78, 16, v78
	v_pk_fma_f32 v[16:17], v[16:17], v[188:189], v[80:81]
	v_pk_fma_f32 v[14:15], v[14:15], v[186:187], v[78:79]
	s_nop 0
	v_cvt_pk_bf16_f32 v14, v14, v15
	v_cvt_pk_bf16_f32 v15, v16, v17
	global_store_dwordx2 v206, v[14:15], s[74:75] offset:96
	v_lshlrev_b32_e32 v84, 16, v83
	v_and_b32_e32 v85, 0xffff0000, v83
	v_and_b32_e32 v83, 0xffff0000, v82
	v_lshlrev_b32_e32 v82, 16, v82
	v_pk_fma_f32 v[20:21], v[20:21], v[176:177], v[84:85]
	v_pk_fma_f32 v[18:19], v[18:19], v[174:175], v[82:83]
	s_nop 0
	v_cvt_pk_bf16_f32 v18, v18, v19
	v_cvt_pk_bf16_f32 v19, v20, v21
	global_store_dwordx2 v207, v[18:19], s[74:75] offset:0
	v_lshlrev_b32_e32 v88, 16, v87
	v_and_b32_e32 v89, 0xffff0000, v87
	v_and_b32_e32 v87, 0xffff0000, v86
	v_lshlrev_b32_e32 v86, 16, v86
	v_pk_fma_f32 v[24:25], v[24:25], v[180:181], v[88:89]
	v_pk_fma_f32 v[22:23], v[22:23], v[178:179], v[86:87]
	s_nop 0
	v_cvt_pk_bf16_f32 v22, v22, v23
	v_cvt_pk_bf16_f32 v23, v24, v25
	global_store_dwordx2 v207, v[22:23], s[74:75] offset:32
	v_lshlrev_b32_e32 v92, 16, v91
	v_and_b32_e32 v93, 0xffff0000, v91
	v_and_b32_e32 v91, 0xffff0000, v90
	v_lshlrev_b32_e32 v90, 16, v90
	v_pk_fma_f32 v[28:29], v[28:29], v[184:185], v[92:93]
	v_pk_fma_f32 v[26:27], v[26:27], v[182:183], v[90:91]
	s_nop 0
	v_cvt_pk_bf16_f32 v26, v26, v27
	v_cvt_pk_bf16_f32 v27, v28, v29
	global_store_dwordx2 v207, v[26:27], s[74:75] offset:64
	v_lshlrev_b32_e32 v96, 16, v95
	v_and_b32_e32 v97, 0xffff0000, v95
	v_and_b32_e32 v95, 0xffff0000, v94
	v_lshlrev_b32_e32 v94, 16, v94
	v_pk_fma_f32 v[32:33], v[32:33], v[188:189], v[96:97]
	v_pk_fma_f32 v[30:31], v[30:31], v[186:187], v[94:95]
	s_nop 0
	v_cvt_pk_bf16_f32 v30, v30, v31
	v_cvt_pk_bf16_f32 v31, v32, v33
	global_store_dwordx2 v207, v[30:31], s[74:75] offset:96
	v_lshlrev_b32_e32 v100, 16, v99
	v_and_b32_e32 v101, 0xffff0000, v99
	v_and_b32_e32 v99, 0xffff0000, v98
	v_lshlrev_b32_e32 v98, 16, v98
	v_pk_fma_f32 v[36:37], v[36:37], v[176:177], v[100:101]
	v_pk_fma_f32 v[34:35], v[34:35], v[174:175], v[98:99]
	s_nop 0
	v_cvt_pk_bf16_f32 v34, v34, v35
	v_cvt_pk_bf16_f32 v35, v36, v37
	global_store_dwordx2 v208, v[34:35], s[74:75] offset:0
	v_lshlrev_b32_e32 v104, 16, v103
	v_and_b32_e32 v105, 0xffff0000, v103
	v_and_b32_e32 v103, 0xffff0000, v102
	v_lshlrev_b32_e32 v102, 16, v102
	v_pk_fma_f32 v[40:41], v[40:41], v[180:181], v[104:105]
	v_pk_fma_f32 v[38:39], v[38:39], v[178:179], v[102:103]
	s_nop 0
	v_cvt_pk_bf16_f32 v38, v38, v39
	v_cvt_pk_bf16_f32 v39, v40, v41
	global_store_dwordx2 v208, v[38:39], s[74:75] offset:32
	v_lshlrev_b32_e32 v108, 16, v107
	v_and_b32_e32 v109, 0xffff0000, v107
	v_and_b32_e32 v107, 0xffff0000, v106
	v_lshlrev_b32_e32 v106, 16, v106
	v_pk_fma_f32 v[44:45], v[44:45], v[184:185], v[108:109]
	v_pk_fma_f32 v[42:43], v[42:43], v[182:183], v[106:107]
	s_nop 0
	v_cvt_pk_bf16_f32 v42, v42, v43
	v_cvt_pk_bf16_f32 v43, v44, v45
	global_store_dwordx2 v208, v[42:43], s[74:75] offset:64
	v_lshlrev_b32_e32 v112, 16, v111
	v_and_b32_e32 v113, 0xffff0000, v111
	v_and_b32_e32 v111, 0xffff0000, v110
	v_lshlrev_b32_e32 v110, 16, v110
	v_pk_fma_f32 v[48:49], v[48:49], v[188:189], v[112:113]
	v_pk_fma_f32 v[46:47], v[46:47], v[186:187], v[110:111]
	s_nop 0
	v_cvt_pk_bf16_f32 v46, v46, v47
	v_cvt_pk_bf16_f32 v47, v48, v49
	global_store_dwordx2 v208, v[46:47], s[74:75] offset:96
	v_lshlrev_b32_e32 v116, 16, v115
	v_and_b32_e32 v117, 0xffff0000, v115
	v_and_b32_e32 v115, 0xffff0000, v114
	v_lshlrev_b32_e32 v114, 16, v114
	v_pk_fma_f32 v[52:53], v[52:53], v[176:177], v[116:117]
	v_pk_fma_f32 v[50:51], v[50:51], v[174:175], v[114:115]
	s_nop 0
	v_cvt_pk_bf16_f32 v50, v50, v51
	v_cvt_pk_bf16_f32 v51, v52, v53
	global_store_dwordx2 v209, v[50:51], s[74:75] offset:0
	v_lshlrev_b32_e32 v120, 16, v119
	v_and_b32_e32 v121, 0xffff0000, v119
	v_and_b32_e32 v119, 0xffff0000, v118
	v_lshlrev_b32_e32 v118, 16, v118
	v_pk_fma_f32 v[56:57], v[56:57], v[180:181], v[120:121]
	v_pk_fma_f32 v[54:55], v[54:55], v[178:179], v[118:119]
	s_nop 0
	v_cvt_pk_bf16_f32 v54, v54, v55
	v_cvt_pk_bf16_f32 v55, v56, v57
	global_store_dwordx2 v209, v[54:55], s[74:75] offset:32
	v_lshlrev_b32_e32 v124, 16, v123
	v_and_b32_e32 v125, 0xffff0000, v123
	v_and_b32_e32 v123, 0xffff0000, v122
	v_lshlrev_b32_e32 v122, 16, v122
	v_pk_fma_f32 v[60:61], v[60:61], v[184:185], v[124:125]
	v_pk_fma_f32 v[58:59], v[58:59], v[182:183], v[122:123]
	s_nop 0
	v_cvt_pk_bf16_f32 v58, v58, v59
	v_cvt_pk_bf16_f32 v59, v60, v61
	global_store_dwordx2 v209, v[58:59], s[74:75] offset:64
	v_lshlrev_b32_e32 v128, 16, v127
	v_and_b32_e32 v129, 0xffff0000, v127
	v_and_b32_e32 v127, 0xffff0000, v126
	v_lshlrev_b32_e32 v126, 16, v126
	v_pk_fma_f32 v[64:65], v[64:65], v[188:189], v[128:129]
	v_pk_fma_f32 v[62:63], v[62:63], v[186:187], v[126:127]
	s_nop 0
	v_cvt_pk_bf16_f32 v62, v62, v63
	v_cvt_pk_bf16_f32 v63, v64, v65
	global_store_dwordx2 v209, v[62:63], s[74:75] offset:96
	s_add_u32 s78, s78, s79
	s_cmp_gt_u32 s78, 31
	s_cbranch_scc1 .Ldn_exit
	s_barrier
	s_branch .Ldn_tile

.LBB0_708:
	s_waitcnt vmcnt(0)
	v_mov_b32_e32 v66, v1
	v_lshlrev_b32_e32 v4, 2, v1
	global_load_dword v100, v4, s[60:61] offset:0
	global_load_dword v101, v4, s[60:61] offset:2048
	global_load_dword v102, v4, s[58:59] offset:0
	global_load_dword v103, v4, s[58:59] offset:2048
	v_add_u32_e32 v99, 0x1000, v4
	global_load_dword v104, v99, s[58:59]
	v_add_u32_e32 v99, 0x1800, v4
	global_load_dword v105, v99, s[58:59]
	v_add_u32_e32 v99, 0x2000, v4
	global_load_dword v106, v99, s[58:59]
	v_add_u32_e32 v99, 0x2800, v4
	global_load_dword v107, v99, s[58:59]
	v_add_u32_e32 v99, 0x3000, v4
	global_load_dword v108, v99, s[58:59]
	v_add_u32_e32 v99, 0x3800, v4
	global_load_dword v109, v99, s[58:59]
	s_waitcnt vmcnt(0)
	v_mul_f32_e32 v110, 0xbfb8aa3b, v100
	v_exp_f32_e32 v110, v110
	s_nop 0
	v_add_f32_e32 v110, 1.0, v110
	v_div_scale_f32 v111, s[10:11], v110, v110, v100
	v_rcp_f32_e32 v112, v111
	v_div_scale_f32 v113, vcc, v100, v110, v100
	v_fma_f32 v114, -v111, v112, 1.0
	v_fmac_f32_e32 v112, v114, v112
	v_mul_f32_e32 v114, v113, v112
	v_fma_f32 v115, -v111, v114, v113
	v_fmac_f32_e32 v114, v115, v112
	v_fma_f32 v111, -v111, v114, v113
	v_div_fmas_f32 v111, v111, v112, v114
	v_div_fixup_f32 v100, v111, v110, v100
	ds_write_b32 v4, v100 offset:0
	v_mul_f32_e32 v110, 0xbfb8aa3b, v101
	v_exp_f32_e32 v110, v110
	s_nop 0
	v_add_f32_e32 v110, 1.0, v110
	v_div_scale_f32 v111, s[10:11], v110, v110, v101
	v_rcp_f32_e32 v112, v111
	v_div_scale_f32 v113, vcc, v101, v110, v101
	v_fma_f32 v114, -v111, v112, 1.0
	v_fmac_f32_e32 v112, v114, v112
	v_mul_f32_e32 v114, v113, v112
	v_fma_f32 v115, -v111, v114, v113
	v_fmac_f32_e32 v114, v115, v112
	v_fma_f32 v111, -v111, v114, v113
	v_div_fmas_f32 v111, v111, v112, v114
	v_div_fixup_f32 v101, v111, v110, v101
	ds_write_b32 v4, v101 offset:2048
	v_mul_f32_e32 v110, 0xbfb8aa3b, v102
	v_exp_f32_e32 v110, v110
	s_nop 0
	v_add_f32_e32 v110, 1.0, v110
	v_div_scale_f32 v111, s[10:11], v110, v110, v102
	v_rcp_f32_e32 v112, v111
	v_div_scale_f32 v113, vcc, v102, v110, v102
	v_fma_f32 v114, -v111, v112, 1.0
	v_fmac_f32_e32 v112, v114, v112
	v_mul_f32_e32 v114, v113, v112
	v_fma_f32 v115, -v111, v114, v113
	v_fmac_f32_e32 v114, v115, v112
	v_fma_f32 v111, -v111, v114, v113
	v_div_fmas_f32 v111, v111, v112, v114
	v_div_fixup_f32 v102, v111, v110, v102
	ds_write_b32 v4, v102 offset:4096
	v_mul_f32_e32 v110, 0xbfb8aa3b, v103
	v_exp_f32_e32 v110, v110
	s_nop 0
	v_add_f32_e32 v110, 1.0, v110
	v_div_scale_f32 v111, s[10:11], v110, v110, v103
	v_rcp_f32_e32 v112, v111
	v_div_scale_f32 v113, vcc, v103, v110, v103
	v_fma_f32 v114, -v111, v112, 1.0
	v_fmac_f32_e32 v112, v114, v112
	v_mul_f32_e32 v114, v113, v112
	v_fma_f32 v115, -v111, v114, v113
	v_fmac_f32_e32 v114, v115, v112
	v_fma_f32 v111, -v111, v114, v113
	v_div_fmas_f32 v111, v111, v112, v114
	v_div_fixup_f32 v103, v111, v110, v103
	ds_write_b32 v4, v103 offset:6144
	v_mul_f32_e32 v110, 0xbfb8aa3b, v104
	v_exp_f32_e32 v110, v110
	s_nop 0
	v_add_f32_e32 v110, 1.0, v110
	v_div_scale_f32 v111, s[10:11], v110, v110, v104
	v_rcp_f32_e32 v112, v111
	v_div_scale_f32 v113, vcc, v104, v110, v104
	v_fma_f32 v114, -v111, v112, 1.0
	v_fmac_f32_e32 v112, v114, v112
	v_mul_f32_e32 v114, v113, v112
	v_fma_f32 v115, -v111, v114, v113
	v_fmac_f32_e32 v114, v115, v112
	v_fma_f32 v111, -v111, v114, v113
	v_div_fmas_f32 v111, v111, v112, v114
	v_div_fixup_f32 v104, v111, v110, v104
	ds_write_b32 v4, v104 offset:8192
	v_mul_f32_e32 v110, 0xbfb8aa3b, v105
	v_exp_f32_e32 v110, v110
	s_nop 0
	v_add_f32_e32 v110, 1.0, v110
	v_div_scale_f32 v111, s[10:11], v110, v110, v105
	v_rcp_f32_e32 v112, v111
	v_div_scale_f32 v113, vcc, v105, v110, v105
	v_fma_f32 v114, -v111, v112, 1.0
	v_fmac_f32_e32 v112, v114, v112
	v_mul_f32_e32 v114, v113, v112
	v_fma_f32 v115, -v111, v114, v113
	v_fmac_f32_e32 v114, v115, v112
	v_fma_f32 v111, -v111, v114, v113
	v_div_fmas_f32 v111, v111, v112, v114
	v_div_fixup_f32 v105, v111, v110, v105
	ds_write_b32 v4, v105 offset:10240
	v_mul_f32_e32 v110, 0xbfb8aa3b, v106
	v_exp_f32_e32 v110, v110
	s_nop 0
	v_add_f32_e32 v110, 1.0, v110
	v_div_scale_f32 v111, s[10:11], v110, v110, v106
	v_rcp_f32_e32 v112, v111
	v_div_scale_f32 v113, vcc, v106, v110, v106
	v_fma_f32 v114, -v111, v112, 1.0
	v_fmac_f32_e32 v112, v114, v112
	v_mul_f32_e32 v114, v113, v112
	v_fma_f32 v115, -v111, v114, v113
	v_fmac_f32_e32 v114, v115, v112
	v_fma_f32 v111, -v111, v114, v113
	v_div_fmas_f32 v111, v111, v112, v114
	v_div_fixup_f32 v106, v111, v110, v106
	ds_write_b32 v4, v106 offset:12288
	v_mul_f32_e32 v110, 0xbfb8aa3b, v107
	v_exp_f32_e32 v110, v110
	s_nop 0
	v_add_f32_e32 v110, 1.0, v110
	v_div_scale_f32 v111, s[10:11], v110, v110, v107
	v_rcp_f32_e32 v112, v111
	v_div_scale_f32 v113, vcc, v107, v110, v107
	v_fma_f32 v114, -v111, v112, 1.0
	v_fmac_f32_e32 v112, v114, v112
	v_mul_f32_e32 v114, v113, v112
	v_fma_f32 v115, -v111, v114, v113
	v_fmac_f32_e32 v114, v115, v112
	v_fma_f32 v111, -v111, v114, v113
	v_div_fmas_f32 v111, v111, v112, v114
	v_div_fixup_f32 v107, v111, v110, v107
	ds_write_b32 v4, v107 offset:14336
	v_mul_f32_e32 v110, 0xbfb8aa3b, v108
	v_exp_f32_e32 v110, v110
	s_nop 0
	v_add_f32_e32 v110, 1.0, v110
	v_div_scale_f32 v111, s[10:11], v110, v110, v108
	v_rcp_f32_e32 v112, v111
	v_div_scale_f32 v113, vcc, v108, v110, v108
	v_fma_f32 v114, -v111, v112, 1.0
	v_fmac_f32_e32 v112, v114, v112
	v_mul_f32_e32 v114, v113, v112
	v_fma_f32 v115, -v111, v114, v113
	v_fmac_f32_e32 v114, v115, v112
	v_fma_f32 v111, -v111, v114, v113
	v_div_fmas_f32 v111, v111, v112, v114
	v_div_fixup_f32 v108, v111, v110, v108
	ds_write_b32 v4, v108 offset:16384
	v_mul_f32_e32 v110, 0xbfb8aa3b, v109
	v_exp_f32_e32 v110, v110
	s_nop 0
	v_add_f32_e32 v110, 1.0, v110
	v_div_scale_f32 v111, s[10:11], v110, v110, v109
	v_rcp_f32_e32 v112, v111
	v_div_scale_f32 v113, vcc, v109, v110, v109
	v_fma_f32 v114, -v111, v112, 1.0
	v_fmac_f32_e32 v112, v114, v112
	v_mul_f32_e32 v114, v113, v112
	v_fma_f32 v115, -v111, v114, v113
	v_fmac_f32_e32 v114, v115, v112
	v_fma_f32 v111, -v111, v114, v113
	v_div_fmas_f32 v111, v111, v112, v114
	v_div_fixup_f32 v109, v111, v110, v109
	ds_write_b32 v4, v109 offset:18432
	s_mov_b64 s[6:7], 0
